# attention key loop software-pipelined by hand (QK of next tile under softmax VALU) + Q/K head-pair slot swizzle by token to spread L2 channels; RWKV consumer packed-f32
# speedup vs baseline: 1.0085x; 1.0085x over previous
; __device__ __forceinline__ unsigned cvt_pk_bf16(float lo, float hi) { unsigned r; asm volatile("v_cvt_pk_bf16_f32 %0, %1, %2" : "=v"(r) : "v"(lo), "v"(hi)); return r; }
;     __device__ __forceinline__ void operator()(const f32x4 (&acc)[2][2][4][2], const Unit& u, int wr, int wc, int fr, int fq) const {
;     ...
;         if (u.pn < 16) {
;             const float qs = u.pn < 8 ? (0.125f * 1.44269504089f) : 1.0f;
;             const int j0 = 16 * (wc & 1) + 4 * fq;
; #pragma unroll
;             for (int ai = 0; ai < 2; ++ai)
; #pragma unroll
;                 for (int m = 0; m < 4; ++m) { const int row = row0 + ai * 128 + m * 16, t = row & 4095;
;                     const f32x4 c4 = *(const f32x4*)(cs + t * 32 + j0), s4 = *(const f32x4*)(sn + t * 32 + j0);
; #pragma unroll
;                     for (int bj = 0; bj < 2; ++bj) { const int hh = 2 * bj + (wc >> 1);
;                         const f32x4 x1 = acc[ai][bj][m][0], x2 = acc[ai][bj][m][1]; float o1[4], o2[4];
; #pragma unroll
;                         for (int i = 0; i < 4; ++i) { o1[i] = (x1[i] * c4[i] - x2[i] * s4[i]) * qs; o2[i] = (x2[i] * c4[i] + x1[i] * s4[i]) * qs; }
;                         u16* dst = QK + (size_t)row * 4096 + u.pn * 256 + 64 * hh + j0;
;                         u32x2 a, b; a[0] = cvt_pk_bf16(o1[0], o1[1]); a[1] = cvt_pk_bf16(o1[2], o1[3]); b[0] = cvt_pk_bf16(o2[0], o2[1]); b[1] = cvt_pk_bf16(o2[2], o2[3]);
;                         *(u32x2*)dst = a; *(u32x2*)(dst + 32) = b; } }
.LBB0_1960:
	s_andn2_b64 vcc, exec, s[30:31]
	s_cbranch_vccnz .LBB0_1953
	v_lshlrev_b32_e32 v132, 7, v148
	v_and_b32_e32 v132, 0x7e780, v132
	v_lshl_add_u64 v[160:161], v[134:135], 0, v[132:133]
	v_lshl_add_u64 v[166:167], v[136:137], 0, v[132:133]
	global_load_dwordx4 v[162:165], v[160:161], off
	s_nop 0
	global_load_dwordx4 v[166:169], v[166:167], off
	s_cmp_lt_i32 s60, 8
	v_ashrrev_i32_e32 v149, 31, v148
	s_cselect_b64 vcc, -1, 0
	s_lshl_b32 s30, s60, 8
	v_lshlrev_b64 v[186:187], 13, v[148:149]
	s_ashr_i32 s31, s30, 31
	v_mov_b32_e32 v172, v124
	v_mov_b32_e32 v173, v120
	v_mov_b32_e32 v174, v120
	v_mov_b32_e32 v175, v124
	v_mov_b32_e32 v120, v125
	v_mov_b32_e32 v124, v121
	v_mov_b32_e32 v176, v126
	v_mov_b32_e32 v177, v122
	v_mov_b32_e32 v178, v122
	v_mov_b32_e32 v122, v127
	v_mov_b32_e32 v180, v116
	v_mov_b32_e32 v181, v112
	v_mov_b32_e32 v182, v112
	v_mov_b32_e32 v183, v116
	v_mov_b32_e32 v112, v117
	v_mov_b32_e32 v116, v113
	v_lshl_add_u64 v[186:187], s[96:97], 0, v[186:187]
	s_lshl_b64 s[30:31], s[30:31], 1
	s_and_b32 s31, s60, 7
	v_and_b32_e32 v238, 7, v170
	v_add_u32_e32 v238, s31, v238
	v_and_b32_e32 v238, 7, v238
	v_lshl_add_u32 v238, v238, 9, v146
	v_mov_b32_e32 v239, 0
	s_and_b32 s30, s60, 8
	s_lshl_b32 s30, s30, 9
	s_mov_b32 s31, 0
	v_mov_b32_e32 v179, v126
	v_mov_b32_e32 v126, v123
	v_lshl_add_u64 v[186:187], v[186:187], 0, s[30:31]
	v_mov_b32_e32 v147, v133
	v_cndmask_b32_e32 v160, 1.0, v159, vcc
	v_lshl_add_u64 v[186:187], v[186:187], 0, s[6:7]
	v_lshl_add_u64 v[186:187], v[186:187], 0, v[238:239]
	v_mov_b32_e32 v185, v114
	v_mov_b32_e32 v184, v118
	s_waitcnt vmcnt(0)
	v_mov_b32_e32 v188, v162
	v_mov_b32_e32 v189, v166
	v_mov_b32_e32 v166, v163
	v_mov_b32_e32 v162, v164
	v_mov_b32_e32 v163, v168
	v_mov_b32_e32 v168, v165
	v_pk_mul_f32 v[164:165], v[172:173], v[188:189]
	v_pk_mul_f32 v[172:173], v[174:175], v[188:189]
	v_pk_mul_f32 v[120:121], v[120:121], v[166:167]
	v_pk_mul_f32 v[124:125], v[124:125], v[166:167]
	v_pk_mul_f32 v[174:175], v[176:177], v[162:163]
	v_pk_mul_f32 v[122:123], v[122:123], v[168:169]
	v_pk_mul_f32 v[112:113], v[112:113], v[166:167]
	v_pk_mul_f32 v[116:117], v[116:117], v[166:167]
	v_pk_mul_f32 v[176:177], v[178:179], v[162:163]
	v_pk_mul_f32 v[126:127], v[126:127], v[168:169]
	v_sub_f32_e32 v132, v164, v165
	v_add_f32_e32 v149, v172, v173
	v_sub_f32_e32 v120, v120, v121
	v_add_f32_e32 v121, v124, v125
	v_sub_f32_e32 v124, v174, v175
	v_sub_f32_e32 v122, v122, v123
	v_sub_f32_e32 v112, v112, v113
	v_add_f32_e32 v113, v116, v117
	v_add_f32_e32 v125, v176, v177
	v_add_f32_e32 v123, v126, v127
	v_mul_f32_e32 v116, v160, v132
	v_mul_f32_e32 v117, v160, v149
	v_mul_f32_e32 v120, v160, v120
	v_mul_f32_e32 v124, v160, v124
	v_mul_f32_e32 v122, v160, v122
	v_mul_f32_e32 v132, v160, v112
	v_mul_f32_e32 v149, v160, v113
	v_cvt_pk_bf16_f32 v112, v116, v120
	v_cvt_pk_bf16_f32 v113, v124, v122
	v_mul_f32_e32 v121, v160, v121
	v_mul_f32_e32 v125, v160, v125
	v_mul_f32_e32 v123, v160, v123
	v_cvt_pk_bf16_f32 v116, v117, v121
	v_cvt_pk_bf16_f32 v117, v125, v123
	global_store_dwordx2 v[186:187], v[112:113], off
	global_store_dwordx2 v[186:187], v[116:117], off offset:64
	v_mov_b32_e32 v112, v114
	v_mov_b32_e32 v113, v118
	v_pk_mul_f32 v[112:113], v[112:113], v[162:163]
	v_mov_b32_e32 v114, v119
	v_add_f32_e32 v112, v112, v113
	v_mul_f32_e32 v117, v160, v112
	v_pk_mul_f32 v[112:113], v[114:115], v[168:169]
	v_mov_b32_e32 v118, v115
	v_sub_f32_e32 v112, v112, v113
	v_pk_mul_f32 v[178:179], v[180:181], v[188:189]
	v_pk_mul_f32 v[166:167], v[184:185], v[162:163]
	v_mul_f32_e32 v114, v160, v112
	v_pk_mul_f32 v[112:113], v[118:119], v[168:169]
	v_pk_mul_f32 v[180:181], v[182:183], v[188:189]
	v_sub_f32_e32 v126, v178, v179
	v_sub_f32_e32 v151, v166, v167
	v_add_f32_e32 v112, v112, v113
	v_add_f32_e32 v127, v180, v181
	v_mul_f32_e32 v126, v160, v126
	v_mul_f32_e32 v116, v160, v151
	v_mul_f32_e32 v115, v160, v112
	v_cvt_pk_bf16_f32 v112, v126, v132
	v_cvt_pk_bf16_f32 v113, v116, v114
	v_or_b32_e32 v120, 16, v148
	v_mul_f32_e32 v127, v160, v127
	v_cvt_pk_bf16_f32 v114, v127, v149
	v_cvt_pk_bf16_f32 v115, v117, v115
	global_store_dwordx2 v[186:187], v[112:113], off offset:256
	global_store_dwordx2 v[186:187], v[114:115], off offset:320
	v_lshlrev_b32_e32 v112, 7, v120
	v_and_b32_e32 v132, 0x7ef80, v112
	v_lshl_add_u64 v[112:113], v[134:135], 0, v[132:133]
	v_lshl_add_u64 v[116:117], v[136:137], 0, v[132:133]
	global_load_dwordx4 v[112:115], v[112:113], off
	s_nop 0
	global_load_dwordx4 v[116:119], v[116:117], off
	v_ashrrev_i32_e32 v121, 31, v120
	v_mov_b32_e32 v122, v108
	v_mov_b32_e32 v123, v104
	v_mov_b32_e32 v124, v104
	v_mov_b32_e32 v125, v108
	v_mov_b32_e32 v104, v109
	v_mov_b32_e32 v108, v105
	v_mov_b32_e32 v126, v110
	v_mov_b32_e32 v127, v106
	v_lshlrev_b64 v[120:121], 13, v[120:121]
	v_mov_b32_e32 v162, v106
	v_mov_b32_e32 v163, v110
	v_mov_b32_e32 v106, v111
	v_mov_b32_e32 v110, v107
	v_lshl_add_u64 v[120:121], s[96:97], 0, v[120:121]
	v_mov_b32_e32 v165, v96
	v_mov_b32_e32 v166, v96
	v_lshl_add_u64 v[120:121], v[120:121], 0, s[30:31]
	v_lshl_add_u64 v[120:121], v[120:121], 0, s[6:7]
	v_lshl_add_u64 v[120:121], v[120:121], 0, v[238:239]
	v_mov_b32_e32 v167, v100
	v_mov_b32_e32 v164, v100
	v_mov_b32_e32 v100, v97
	v_ashrrev_i32_e32 v151, 31, v150
	s_waitcnt vmcnt(0)
; __device__ __forceinline__ unsigned cvt_pk_bf16(float lo, float hi) { unsigned r; asm volatile("v_cvt_pk_bf16_f32 %0, %1, %2" : "=v"(r) : "v"(lo), "v"(hi)); return r; }
;     __device__ __forceinline__ void operator()(const f32x4 (&acc)[2][2][4][2], const Unit& u, int wr, int wc, int fr, int fq) const {
;     ...
;         if (u.pn < 16) {
;             const float qs = u.pn < 8 ? (0.125f * 1.44269504089f) : 1.0f;
;             const int j0 = 16 * (wc & 1) + 4 * fq;
; #pragma unroll
;             for (int ai = 0; ai < 2; ++ai)
; #pragma unroll
;                 for (int m = 0; m < 4; ++m) { const int row = row0 + ai * 128 + m * 16, t = row & 4095;
;                     const f32x4 c4 = *(const f32x4*)(cs + t * 32 + j0), s4 = *(const f32x4*)(sn + t * 32 + j0);
; #pragma unroll
;                     for (int bj = 0; bj < 2; ++bj) { const int hh = 2 * bj + (wc >> 1);
;                         const f32x4 x1 = acc[ai][bj][m][0], x2 = acc[ai][bj][m][1]; float o1[4], o2[4];
; #pragma unroll
;                         for (int i = 0; i < 4; ++i) { o1[i] = (x1[i] * c4[i] - x2[i] * s4[i]) * qs; o2[i] = (x2[i] * c4[i] + x1[i] * s4[i]) * qs; }
;                         u16* dst = QK + (size_t)row * 4096 + u.pn * 256 + 64 * hh + j0;
;                         u32x2 a, b; a[0] = cvt_pk_bf16(o1[0], o1[1]); a[1] = cvt_pk_bf16(o1[2], o1[3]); b[0] = cvt_pk_bf16(o2[0], o2[1]); b[1] = cvt_pk_bf16(o2[2], o2[3]);
;                         *(u32x2*)dst = a; *(u32x2*)(dst + 32) = b; } }
	v_mov_b32_e32 v168, v112
	v_mov_b32_e32 v169, v116
	v_mov_b32_e32 v116, v113
	v_mov_b32_e32 v112, v114
	v_mov_b32_e32 v113, v118
	v_mov_b32_e32 v118, v115
	v_pk_mul_f32 v[114:115], v[122:123], v[168:169]
	v_pk_mul_f32 v[122:123], v[124:125], v[168:169]
	v_pk_mul_f32 v[104:105], v[104:105], v[116:117]
	v_pk_mul_f32 v[108:109], v[108:109], v[116:117]
	v_pk_mul_f32 v[124:125], v[126:127], v[112:113]
	v_pk_mul_f32 v[106:107], v[106:107], v[118:119]
	v_pk_mul_f32 v[110:111], v[110:111], v[118:119]
	v_sub_f32_e32 v96, v114, v115
	v_add_f32_e32 v114, v122, v123
	v_sub_f32_e32 v104, v104, v105
	v_add_f32_e32 v105, v108, v109
	v_sub_f32_e32 v108, v124, v125
	v_pk_mul_f32 v[126:127], v[162:163], v[112:113]
	v_sub_f32_e32 v106, v106, v107
	v_add_f32_e32 v107, v110, v111
	v_mul_f32_e32 v111, v160, v114
	v_mul_f32_e32 v104, v160, v104
	v_mul_f32_e32 v114, v160, v105
	v_mul_f32_e32 v105, v160, v108
	v_add_f32_e32 v109, v126, v127
	v_mul_f32_e32 v96, v160, v96
	v_mul_f32_e32 v106, v160, v106
	v_mul_f32_e32 v107, v160, v107
	v_cvt_pk_bf16_f32 v104, v96, v104
	v_cvt_pk_bf16_f32 v105, v105, v106
	v_mul_f32_e32 v108, v160, v109
	v_cvt_pk_bf16_f32 v106, v111, v114
	v_cvt_pk_bf16_f32 v107, v108, v107
	global_store_dwordx2 v[120:121], v[104:105], off
	global_store_dwordx2 v[120:121], v[106:107], off offset:64
	v_pk_mul_f32 v[104:105], v[166:167], v[168:169]
	v_pk_mul_f32 v[162:163], v[164:165], v[168:169]
	v_add_f32_e32 v96, v104, v105
	v_mul_f32_e32 v106, v160, v96
	v_mov_b32_e32 v96, v101
	v_pk_mul_f32 v[104:105], v[96:97], v[116:117]
	v_sub_f32_e32 v110, v162, v163
	v_sub_f32_e32 v96, v104, v105
	v_mul_f32_e32 v104, v160, v96
	v_pk_mul_f32 v[96:97], v[100:101], v[116:117]
	v_mul_f32_e32 v109, v160, v110
	v_add_f32_e32 v96, v96, v97
	v_mul_f32_e32 v100, v160, v96
	v_mov_b32_e32 v96, v102
	v_mov_b32_e32 v97, v98
	v_pk_mul_f32 v[96:97], v[96:97], v[112:113]
	v_mov_b32_e32 v107, v88
	v_sub_f32_e32 v96, v96, v97
	v_mul_f32_e32 v101, v160, v96
	v_mov_b32_e32 v96, v98
	v_mov_b32_e32 v97, v102
	v_pk_mul_f32 v[96:97], v[96:97], v[112:113]
	v_mov_b32_e32 v98, v103
	v_add_f32_e32 v96, v96, v97
	v_mul_f32_e32 v105, v160, v96
	v_pk_mul_f32 v[96:97], v[98:99], v[118:119]
	v_mov_b32_e32 v102, v99
	v_sub_f32_e32 v96, v96, v97
	v_mul_f32_e32 v98, v160, v96
	v_pk_mul_f32 v[96:97], v[102:103], v[118:119]
	v_mov_b32_e32 v108, v88
	v_add_f32_e32 v96, v96, v97
	v_mul_f32_e32 v99, v160, v96
	v_cvt_pk_bf16_f32 v96, v109, v104
	v_cvt_pk_bf16_f32 v97, v101, v98
	v_or_b32_e32 v104, 32, v148
	v_cvt_pk_bf16_f32 v98, v106, v100
	v_cvt_pk_bf16_f32 v99, v105, v99
	global_store_dwordx2 v[120:121], v[96:97], off offset:256
	global_store_dwordx2 v[120:121], v[98:99], off offset:320
	v_lshlrev_b32_e32 v96, 7, v104
	v_and_b32_e32 v132, 0x7f780, v96
	v_lshl_add_u64 v[96:97], v[134:135], 0, v[132:133]
	v_lshl_add_u64 v[100:101], v[136:137], 0, v[132:133]
	global_load_dwordx4 v[96:99], v[96:97], off
	s_nop 0
	global_load_dwordx4 v[100:103], v[100:101], off
	v_mov_b32_e32 v106, v92
	v_mov_b32_e32 v109, v92
	v_mov_b32_e32 v88, v93
	v_mov_b32_e32 v92, v89
	v_mov_b32_e32 v110, v94
	v_mov_b32_e32 v111, v90
	v_mov_b32_e32 v112, v90
	v_mov_b32_e32 v113, v94
	v_mov_b32_e32 v90, v95
	v_mov_b32_e32 v94, v91
	v_ashrrev_i32_e32 v105, 31, v104
	v_lshlrev_b64 v[104:105], 13, v[104:105]
	s_waitcnt vmcnt(0)
	v_mov_b32_e32 v114, v96
	v_mov_b32_e32 v115, v100
	v_mov_b32_e32 v100, v97
	v_mov_b32_e32 v96, v98
	v_mov_b32_e32 v97, v102
	v_mov_b32_e32 v102, v99
	v_pk_mul_f32 v[98:99], v[106:107], v[114:115]
	v_pk_mul_f32 v[106:107], v[108:109], v[114:115]
	v_pk_mul_f32 v[88:89], v[88:89], v[100:101]
	v_pk_mul_f32 v[92:93], v[92:93], v[100:101]
	v_pk_mul_f32 v[90:91], v[90:91], v[102:103]
	v_pk_mul_f32 v[94:95], v[94:95], v[102:103]
	v_sub_f32_e32 v98, v98, v99
	v_add_f32_e32 v99, v106, v107
	v_sub_f32_e32 v88, v88, v89
	v_add_f32_e32 v89, v92, v93
	v_sub_f32_e32 v90, v90, v91
	v_mul_f32_e32 v91, v160, v98
	v_mul_f32_e32 v98, v160, v99
	v_mul_f32_e32 v99, v160, v88
	v_add_f32_e32 v88, v94, v95
	v_mul_f32_e32 v106, v160, v89
	v_mul_f32_e32 v94, v160, v88
	v_lshl_add_u64 v[88:89], s[96:97], 0, v[104:105]
	v_pk_mul_f32 v[108:109], v[110:111], v[96:97]
	v_pk_mul_f32 v[110:111], v[112:113], v[96:97]
	v_lshl_add_u64 v[88:89], v[88:89], 0, s[30:31]
	v_sub_f32_e32 v92, v108, v109
	v_add_f32_e32 v93, v110, v111
	v_lshl_add_u64 v[88:89], v[88:89], 0, s[6:7]
	v_mul_f32_e32 v92, v160, v92
	v_mul_f32_e32 v93, v160, v93
	v_mul_f32_e32 v107, v160, v90
	v_lshl_add_u64 v[88:89], v[88:89], 0, v[238:239]
	v_cvt_pk_bf16_f32 v90, v91, v99
	v_cvt_pk_bf16_f32 v91, v92, v107
	v_cvt_pk_bf16_f32 v92, v98, v106
	v_cvt_pk_bf16_f32 v93, v93, v94
	global_store_dwordx2 v[88:89], v[90:91], off
	global_store_dwordx2 v[88:89], v[92:93], off offset:64
	v_mov_b32_e32 v90, v84
	v_mov_b32_e32 v91, v80
	v_pk_mul_f32 v[90:91], v[90:91], v[114:115]
	v_mov_b32_e32 v94, v78
	v_sub_f32_e32 v90, v90, v91
	v_mul_f32_e32 v92, v160, v90
	v_mov_b32_e32 v90, v80
	v_mov_b32_e32 v91, v84
	v_pk_mul_f32 v[90:91], v[90:91], v[114:115]
	v_mov_b32_e32 v84, v81
	v_add_f32_e32 v80, v90, v91
	v_mul_f32_e32 v93, v160, v80
	v_mov_b32_e32 v80, v85
	v_pk_mul_f32 v[90:91], v[80:81], v[100:101]
	v_mov_b32_e32 v95, v74
	v_sub_f32_e32 v80, v90, v91
	v_mul_f32_e32 v90, v160, v80
	v_pk_mul_f32 v[80:81], v[84:85], v[100:101]
	s_nop 0
	v_add_f32_e32 v80, v80, v81
	v_mul_f32_e32 v84, v160, v80
	v_mov_b32_e32 v80, v86
	v_mov_b32_e32 v81, v82
	v_pk_mul_f32 v[80:81], v[80:81], v[96:97]
	s_nop 0
	v_sub_f32_e32 v80, v80, v81
	v_mul_f32_e32 v85, v160, v80
	v_mov_b32_e32 v80, v82
	v_mov_b32_e32 v81, v86
	v_pk_mul_f32 v[80:81], v[80:81], v[96:97]
	v_mov_b32_e32 v82, v87
	v_add_f32_e32 v80, v80, v81
	v_mul_f32_e32 v91, v160, v80
	v_pk_mul_f32 v[80:81], v[82:83], v[102:103]
	v_mov_b32_e32 v86, v83
	v_sub_f32_e32 v80, v80, v81
	v_mul_f32_e32 v82, v160, v80
	v_pk_mul_f32 v[80:81], v[86:87], v[102:103]
	s_nop 0
	v_add_f32_e32 v80, v80, v81
	v_mul_f32_e32 v83, v160, v80
	v_cvt_pk_bf16_f32 v80, v92, v90
	v_cvt_pk_bf16_f32 v81, v85, v82
	v_cvt_pk_bf16_f32 v82, v93, v84
	v_cvt_pk_bf16_f32 v83, v91, v83
	global_store_dwordx2 v[88:89], v[80:81], off offset:256
	global_store_dwordx2 v[88:89], v[82:83], off offset:320
	v_or_b32_e32 v88, 48, v148
	v_lshlrev_b32_e32 v80, 7, v88
	v_and_b32_e32 v132, 0x7ff80, v80
	v_lshl_add_u64 v[80:81], v[134:135], 0, v[132:133]
	v_lshl_add_u64 v[84:85], v[136:137], 0, v[132:133]
	global_load_dwordx4 v[80:83], v[80:81], off
	s_nop 0
	global_load_dwordx4 v[84:87], v[84:85], off
	v_mov_b32_e32 v90, v76
	v_mov_b32_e32 v91, v72
	v_mov_b32_e32 v92, v72
	v_mov_b32_e32 v93, v76
	v_mov_b32_e32 v72, v77
	v_mov_b32_e32 v76, v73
	v_ashrrev_i32_e32 v89, 31, v88
	v_lshlrev_b64 v[88:89], 13, v[88:89]
	s_waitcnt vmcnt(0)
; __device__ __forceinline__ unsigned cvt_pk_bf16(float lo, float hi) { unsigned r; asm volatile("v_cvt_pk_bf16_f32 %0, %1, %2" : "=v"(r) : "v"(lo), "v"(hi)); return r; }
;     __device__ __forceinline__ void operator()(const f32x4 (&acc)[2][2][4][2], const Unit& u, int wr, int wc, int fr, int fq) const {
;     ...
;         if (u.pn < 16) {
;             const float qs = u.pn < 8 ? (0.125f * 1.44269504089f) : 1.0f;
;             const int j0 = 16 * (wc & 1) + 4 * fq;
; #pragma unroll
;             for (int ai = 0; ai < 2; ++ai)
; #pragma unroll
;                 for (int m = 0; m < 4; ++m) { const int row = row0 + ai * 128 + m * 16, t = row & 4095;
;                     const f32x4 c4 = *(const f32x4*)(cs + t * 32 + j0), s4 = *(const f32x4*)(sn + t * 32 + j0);
; #pragma unroll
;                     for (int bj = 0; bj < 2; ++bj) { const int hh = 2 * bj + (wc >> 1);
;                         const f32x4 x1 = acc[ai][bj][m][0], x2 = acc[ai][bj][m][1]; float o1[4], o2[4];
; #pragma unroll
;                         for (int i = 0; i < 4; ++i) { o1[i] = (x1[i] * c4[i] - x2[i] * s4[i]) * qs; o2[i] = (x2[i] * c4[i] + x1[i] * s4[i]) * qs; }
;                         u16* dst = QK + (size_t)row * 4096 + u.pn * 256 + 64 * hh + j0;
;                         u32x2 a, b; a[0] = cvt_pk_bf16(o1[0], o1[1]); a[1] = cvt_pk_bf16(o1[2], o1[3]); b[0] = cvt_pk_bf16(o2[0], o2[1]); b[1] = cvt_pk_bf16(o2[2], o2[3]);
;                         *(u32x2*)dst = a; *(u32x2*)(dst + 32) = b; } }
	v_mov_b32_e32 v96, v80
	v_mov_b32_e32 v97, v84
	v_mov_b32_e32 v84, v81
	v_pk_mul_f32 v[90:91], v[90:91], v[96:97]
	v_pk_mul_f32 v[92:93], v[92:93], v[96:97]
	v_pk_mul_f32 v[72:73], v[72:73], v[84:85]
	v_pk_mul_f32 v[76:77], v[76:77], v[84:85]
	v_sub_f32_e32 v81, v90, v91
	v_mov_b32_e32 v80, v82
	v_add_f32_e32 v82, v92, v93
	v_sub_f32_e32 v72, v72, v73
	v_add_f32_e32 v73, v76, v77
	v_mul_f32_e32 v76, v160, v81
	v_mov_b32_e32 v81, v86
	v_mul_f32_e32 v77, v160, v82
	v_mul_f32_e32 v82, v160, v72
	v_mul_f32_e32 v90, v160, v73
	v_pk_mul_f32 v[72:73], v[94:95], v[80:81]
	v_mov_b32_e32 v86, v83
	v_sub_f32_e32 v72, v72, v73
	v_mul_f32_e32 v91, v160, v72
	v_mov_b32_e32 v72, v74
	v_mov_b32_e32 v73, v78
	v_pk_mul_f32 v[72:73], v[72:73], v[80:81]
	v_mov_b32_e32 v74, v79
	v_add_f32_e32 v72, v72, v73
	v_mul_f32_e32 v92, v160, v72
	v_pk_mul_f32 v[72:73], v[74:75], v[86:87]
	v_mov_b32_e32 v78, v75
	v_sub_f32_e32 v72, v72, v73
	v_mul_f32_e32 v83, v160, v72
	v_pk_mul_f32 v[72:73], v[78:79], v[86:87]
	v_cvt_pk_bf16_f32 v74, v76, v82
	v_cvt_pk_bf16_f32 v75, v91, v83
	v_cvt_pk_bf16_f32 v76, v77, v90
	s_nop 0
	v_add_f32_e32 v72, v72, v73
	v_mul_f32_e32 v78, v160, v72
	v_lshl_add_u64 v[72:73], s[96:97], 0, v[88:89]
	v_lshl_add_u64 v[72:73], v[72:73], 0, s[30:31]
	v_lshl_add_u64 v[72:73], v[72:73], 0, s[6:7]
	v_lshl_add_u64 v[72:73], v[72:73], 0, v[238:239]
	v_cvt_pk_bf16_f32 v77, v92, v78
	global_store_dwordx2 v[72:73], v[74:75], off
	global_store_dwordx2 v[72:73], v[76:77], off offset:64
	v_mov_b32_e32 v74, v68
	v_mov_b32_e32 v75, v64
	v_pk_mul_f32 v[74:75], v[74:75], v[96:97]
	s_nop 0
	v_sub_f32_e32 v74, v74, v75
	v_mul_f32_e32 v76, v160, v74
	v_mov_b32_e32 v74, v64
	v_mov_b32_e32 v75, v68
	v_pk_mul_f32 v[74:75], v[74:75], v[96:97]
	v_mov_b32_e32 v68, v65
	v_add_f32_e32 v64, v74, v75
	v_mul_f32_e32 v77, v160, v64
	v_mov_b32_e32 v64, v69
	v_pk_mul_f32 v[74:75], v[64:65], v[84:85]
	s_nop 0
	v_sub_f32_e32 v64, v74, v75
	v_mul_f32_e32 v74, v160, v64
	v_pk_mul_f32 v[64:65], v[68:69], v[84:85]
	s_nop 0
	v_add_f32_e32 v64, v64, v65
	v_mul_f32_e32 v68, v160, v64
	v_mov_b32_e32 v64, v70
	v_mov_b32_e32 v65, v66
	v_pk_mul_f32 v[64:65], v[64:65], v[80:81]
	s_nop 0
	v_sub_f32_e32 v64, v64, v65
	v_mul_f32_e32 v69, v160, v64
	v_mov_b32_e32 v64, v66
	v_mov_b32_e32 v65, v70
	v_pk_mul_f32 v[64:65], v[64:65], v[80:81]
	v_mov_b32_e32 v66, v71
	v_add_f32_e32 v64, v64, v65
	v_mul_f32_e32 v75, v160, v64
	v_pk_mul_f32 v[64:65], v[66:67], v[86:87]
	v_mov_b32_e32 v70, v67
	v_sub_f32_e32 v64, v64, v65
	v_mul_f32_e32 v66, v160, v64
	v_pk_mul_f32 v[64:65], v[70:71], v[86:87]
	s_nop 0
	v_add_f32_e32 v64, v64, v65
	v_mul_f32_e32 v67, v160, v64
	v_cvt_pk_bf16_f32 v64, v76, v74
	v_cvt_pk_bf16_f32 v65, v69, v66
	v_cvt_pk_bf16_f32 v66, v77, v68
	v_cvt_pk_bf16_f32 v67, v75, v67
	global_store_dwordx2 v[72:73], v[64:65], off offset:256
	global_store_dwordx2 v[72:73], v[66:67], off offset:320
	v_lshlrev_b32_e32 v64, 7, v150
	v_and_b32_e32 v132, 0x7e780, v64
	v_lshl_add_u64 v[64:65], v[134:135], 0, v[132:133]
	v_lshl_add_u64 v[68:69], v[136:137], 0, v[132:133]
	global_load_dwordx4 v[64:67], v[64:65], off
	s_nop 0
	global_load_dwordx4 v[68:71], v[68:69], off
	v_mov_b32_e32 v72, v60
	v_mov_b32_e32 v73, v56
	v_mov_b32_e32 v74, v56
	v_mov_b32_e32 v75, v60
	v_mov_b32_e32 v60, v57
	v_lshlrev_b64 v[76:77], 13, v[150:151]
	s_waitcnt vmcnt(0)
	v_mov_b32_e32 v78, v64
	v_mov_b32_e32 v79, v68
	v_pk_mul_f32 v[72:73], v[72:73], v[78:79]
	v_mov_b32_e32 v68, v65
	v_sub_f32_e32 v56, v72, v73
	v_pk_mul_f32 v[72:73], v[74:75], v[78:79]
	v_mul_f32_e32 v80, v160, v56
	v_add_f32_e32 v56, v72, v73
	v_mul_f32_e32 v72, v160, v56
	v_mov_b32_e32 v56, v61
	v_pk_mul_f32 v[64:65], v[56:57], v[68:69]
	s_nop 0
	v_sub_f32_e32 v56, v64, v65
	v_mul_f32_e32 v64, v160, v56
	v_pk_mul_f32 v[56:57], v[60:61], v[68:69]
	v_mov_b32_e32 v60, v66
	v_add_f32_e32 v56, v56, v57
	v_mul_f32_e32 v65, v160, v56
	v_mov_b32_e32 v56, v62
	v_mov_b32_e32 v57, v58
	v_mov_b32_e32 v61, v70
	v_pk_mul_f32 v[56:57], v[56:57], v[60:61]
	v_mov_b32_e32 v70, v67
	v_sub_f32_e32 v56, v56, v57
	v_mul_f32_e32 v66, v160, v56
	v_mov_b32_e32 v56, v58
	v_mov_b32_e32 v57, v62
	v_pk_mul_f32 v[56:57], v[56:57], v[60:61]
	v_mov_b32_e32 v58, v63
	v_add_f32_e32 v56, v56, v57
	v_mul_f32_e32 v73, v160, v56
	v_pk_mul_f32 v[56:57], v[58:59], v[70:71]
	v_mov_b32_e32 v62, v59
	v_sub_f32_e32 v56, v56, v57
	v_mul_f32_e32 v67, v160, v56
	v_pk_mul_f32 v[56:57], v[62:63], v[70:71]
	v_cvt_pk_bf16_f32 v58, v80, v64
	v_cvt_pk_bf16_f32 v59, v66, v67
	v_cvt_pk_bf16_f32 v62, v72, v65
	s_nop 0
	v_add_f32_e32 v56, v56, v57
	v_mul_f32_e32 v63, v160, v56
	v_lshl_add_u64 v[56:57], s[96:97], 0, v[76:77]
	v_lshl_add_u64 v[56:57], v[56:57], 0, s[30:31]
	v_lshl_add_u64 v[56:57], v[56:57], 0, s[6:7]
	v_lshl_add_u64 v[56:57], v[56:57], 0, v[238:239]
	v_cvt_pk_bf16_f32 v63, v73, v63
	global_store_dwordx2 v[56:57], v[58:59], off
	global_store_dwordx2 v[56:57], v[62:63], off offset:64
	v_mov_b32_e32 v58, v52
	v_mov_b32_e32 v59, v48
	v_pk_mul_f32 v[58:59], v[58:59], v[78:79]
	s_nop 0
	v_sub_f32_e32 v58, v58, v59
	v_mul_f32_e32 v62, v160, v58
	v_mov_b32_e32 v58, v48
	v_mov_b32_e32 v59, v52
	v_pk_mul_f32 v[58:59], v[58:59], v[78:79]
	v_mov_b32_e32 v52, v49
	v_add_f32_e32 v48, v58, v59
	v_mul_f32_e32 v63, v160, v48
	v_mov_b32_e32 v48, v53
	v_pk_mul_f32 v[58:59], v[48:49], v[68:69]
	s_nop 0
	v_sub_f32_e32 v48, v58, v59
	v_mul_f32_e32 v58, v160, v48
	v_pk_mul_f32 v[48:49], v[52:53], v[68:69]
	s_nop 0
	v_add_f32_e32 v48, v48, v49
	v_mul_f32_e32 v52, v160, v48
	v_mov_b32_e32 v48, v54
	v_mov_b32_e32 v49, v50
	v_pk_mul_f32 v[48:49], v[48:49], v[60:61]
	s_nop 0
	v_sub_f32_e32 v48, v48, v49
	v_mul_f32_e32 v53, v160, v48
	v_mov_b32_e32 v48, v50
	v_mov_b32_e32 v49, v54
	v_pk_mul_f32 v[48:49], v[48:49], v[60:61]
	v_mov_b32_e32 v50, v55
	v_add_f32_e32 v48, v48, v49
	v_mul_f32_e32 v59, v160, v48
	v_pk_mul_f32 v[48:49], v[50:51], v[70:71]
	v_mov_b32_e32 v54, v51
	v_sub_f32_e32 v48, v48, v49
	v_mul_f32_e32 v50, v160, v48
	v_pk_mul_f32 v[48:49], v[54:55], v[70:71]
	s_nop 0
	v_add_f32_e32 v48, v48, v49
	v_mul_f32_e32 v51, v160, v48
	v_cvt_pk_bf16_f32 v48, v62, v58
	v_cvt_pk_bf16_f32 v49, v53, v50
	v_cvt_pk_bf16_f32 v50, v63, v52
	v_cvt_pk_bf16_f32 v51, v59, v51
	global_store_dwordx2 v[56:57], v[48:49], off offset:256
	global_store_dwordx2 v[56:57], v[50:51], off offset:320
	v_add_u32_e32 v56, 0x90, v148
	v_lshlrev_b32_e32 v48, 7, v56
	v_and_b32_e32 v132, 0x7ef80, v48
	v_lshl_add_u64 v[48:49], v[134:135], 0, v[132:133]
	v_lshl_add_u64 v[52:53], v[136:137], 0, v[132:133]
	global_load_dwordx4 v[48:51], v[48:49], off
	s_nop 0
	global_load_dwordx4 v[52:55], v[52:53], off
	v_mov_b32_e32 v58, v44
	v_mov_b32_e32 v59, v40
	v_ashrrev_i32_e32 v57, 31, v56
	v_lshlrev_b64 v[56:57], 13, v[56:57]
	s_waitcnt vmcnt(0)
; __device__ __forceinline__ unsigned cvt_pk_bf16(float lo, float hi) { unsigned r; asm volatile("v_cvt_pk_bf16_f32 %0, %1, %2" : "=v"(r) : "v"(lo), "v"(hi)); return r; }
;     __device__ __forceinline__ void operator()(const f32x4 (&acc)[2][2][4][2], const Unit& u, int wr, int wc, int fr, int fq) const {
;     ...
;         if (u.pn < 16) {
;             const float qs = u.pn < 8 ? (0.125f * 1.44269504089f) : 1.0f;
;             const int j0 = 16 * (wc & 1) + 4 * fq;
; #pragma unroll
;             for (int ai = 0; ai < 2; ++ai)
; #pragma unroll
;                 for (int m = 0; m < 4; ++m) { const int row = row0 + ai * 128 + m * 16, t = row & 4095;
;                     const f32x4 c4 = *(const f32x4*)(cs + t * 32 + j0), s4 = *(const f32x4*)(sn + t * 32 + j0);
; #pragma unroll
;                     for (int bj = 0; bj < 2; ++bj) { const int hh = 2 * bj + (wc >> 1);
;                         const f32x4 x1 = acc[ai][bj][m][0], x2 = acc[ai][bj][m][1]; float o1[4], o2[4];
; #pragma unroll
;                         for (int i = 0; i < 4; ++i) { o1[i] = (x1[i] * c4[i] - x2[i] * s4[i]) * qs; o2[i] = (x2[i] * c4[i] + x1[i] * s4[i]) * qs; }
;                         u16* dst = QK + (size_t)row * 4096 + u.pn * 256 + 64 * hh + j0;
;                         u32x2 a, b; a[0] = cvt_pk_bf16(o1[0], o1[1]); a[1] = cvt_pk_bf16(o1[2], o1[3]); b[0] = cvt_pk_bf16(o2[0], o2[1]); b[1] = cvt_pk_bf16(o2[2], o2[3]);
;                         *(u32x2*)dst = a; *(u32x2*)(dst + 32) = b; } }
	v_mov_b32_e32 v60, v48
	v_mov_b32_e32 v61, v52
	v_pk_mul_f32 v[58:59], v[58:59], v[60:61]
	v_mov_b32_e32 v52, v49
	v_sub_f32_e32 v48, v58, v59
	v_mov_b32_e32 v58, v40
	v_mov_b32_e32 v59, v44
	v_pk_mul_f32 v[58:59], v[58:59], v[60:61]
	v_mul_f32_e32 v62, v160, v48
	v_add_f32_e32 v40, v58, v59
	v_mul_f32_e32 v58, v160, v40
	v_mov_b32_e32 v40, v45
	v_pk_mul_f32 v[48:49], v[40:41], v[52:53]
	v_mov_b32_e32 v44, v41
	v_sub_f32_e32 v40, v48, v49
	v_mul_f32_e32 v48, v160, v40
	v_pk_mul_f32 v[40:41], v[44:45], v[52:53]
	v_mov_b32_e32 v44, v50
	v_add_f32_e32 v40, v40, v41
	v_mul_f32_e32 v49, v160, v40
	v_mov_b32_e32 v40, v46
	v_mov_b32_e32 v41, v42
	v_mov_b32_e32 v45, v54
	v_pk_mul_f32 v[40:41], v[40:41], v[44:45]
	v_mov_b32_e32 v54, v51
	v_sub_f32_e32 v40, v40, v41
	v_mul_f32_e32 v50, v160, v40
	v_mov_b32_e32 v40, v42
	v_mov_b32_e32 v41, v46
	v_pk_mul_f32 v[40:41], v[40:41], v[44:45]
	v_mov_b32_e32 v42, v47
	v_add_f32_e32 v40, v40, v41
	v_mul_f32_e32 v59, v160, v40
	v_pk_mul_f32 v[40:41], v[42:43], v[54:55]
	v_mov_b32_e32 v46, v43
	v_sub_f32_e32 v40, v40, v41
	v_mul_f32_e32 v51, v160, v40
	v_pk_mul_f32 v[40:41], v[46:47], v[54:55]
	v_cvt_pk_bf16_f32 v42, v62, v48
	v_cvt_pk_bf16_f32 v43, v50, v51
	v_cvt_pk_bf16_f32 v46, v58, v49
	s_nop 0
	v_add_f32_e32 v40, v40, v41
	v_mul_f32_e32 v47, v160, v40
	v_lshl_add_u64 v[40:41], s[96:97], 0, v[56:57]
	v_lshl_add_u64 v[40:41], v[40:41], 0, s[30:31]
	v_lshl_add_u64 v[40:41], v[40:41], 0, s[6:7]
	v_lshl_add_u64 v[40:41], v[40:41], 0, v[238:239]
	v_cvt_pk_bf16_f32 v47, v59, v47
	global_store_dwordx2 v[40:41], v[42:43], off
	global_store_dwordx2 v[40:41], v[46:47], off offset:64
	v_mov_b32_e32 v42, v36
	v_mov_b32_e32 v43, v32
	v_pk_mul_f32 v[42:43], v[42:43], v[60:61]
	s_nop 0
	v_sub_f32_e32 v42, v42, v43
	v_mul_f32_e32 v46, v160, v42
	v_mov_b32_e32 v42, v32
	v_mov_b32_e32 v43, v36
	v_pk_mul_f32 v[42:43], v[42:43], v[60:61]
	v_mov_b32_e32 v36, v33
	v_add_f32_e32 v32, v42, v43
	v_mul_f32_e32 v47, v160, v32
	v_mov_b32_e32 v32, v37
	v_pk_mul_f32 v[42:43], v[32:33], v[52:53]
	s_nop 0
	v_sub_f32_e32 v32, v42, v43
	v_mul_f32_e32 v42, v160, v32
	v_pk_mul_f32 v[32:33], v[36:37], v[52:53]
	s_nop 0
	v_add_f32_e32 v32, v32, v33
	v_mul_f32_e32 v36, v160, v32
	v_mov_b32_e32 v32, v38
	v_mov_b32_e32 v33, v34
	v_pk_mul_f32 v[32:33], v[32:33], v[44:45]
	s_nop 0
	v_sub_f32_e32 v32, v32, v33
	v_mul_f32_e32 v37, v160, v32
	v_mov_b32_e32 v32, v34
	v_mov_b32_e32 v33, v38
	v_pk_mul_f32 v[32:33], v[32:33], v[44:45]
	v_mov_b32_e32 v34, v39
	v_add_f32_e32 v32, v32, v33
	v_mul_f32_e32 v43, v160, v32
	v_pk_mul_f32 v[32:33], v[34:35], v[54:55]
	v_mov_b32_e32 v38, v35
	v_sub_f32_e32 v32, v32, v33
	v_mul_f32_e32 v34, v160, v32
	v_pk_mul_f32 v[32:33], v[38:39], v[54:55]
	s_nop 0
	v_add_f32_e32 v32, v32, v33
	v_mul_f32_e32 v35, v160, v32
	v_cvt_pk_bf16_f32 v32, v46, v42
	v_cvt_pk_bf16_f32 v33, v37, v34
	v_cvt_pk_bf16_f32 v34, v47, v36
	v_cvt_pk_bf16_f32 v35, v43, v35
	global_store_dwordx2 v[40:41], v[32:33], off offset:256
	global_store_dwordx2 v[40:41], v[34:35], off offset:320
	v_add_u32_e32 v40, 0xa0, v148
	v_lshlrev_b32_e32 v32, 7, v40
	v_and_b32_e32 v132, 0x7f780, v32
	v_lshl_add_u64 v[32:33], v[134:135], 0, v[132:133]
	v_lshl_add_u64 v[36:37], v[136:137], 0, v[132:133]
	global_load_dwordx4 v[32:35], v[32:33], off
	s_nop 0
	global_load_dwordx4 v[36:39], v[36:37], off
	v_mov_b32_e32 v42, v28
	v_mov_b32_e32 v43, v24
	v_ashrrev_i32_e32 v41, 31, v40
	v_lshlrev_b64 v[40:41], 13, v[40:41]
	s_waitcnt vmcnt(0)
; __device__ __forceinline__ unsigned cvt_pk_bf16(float lo, float hi) { unsigned r; asm volatile("v_cvt_pk_bf16_f32 %0, %1, %2" : "=v"(r) : "v"(lo), "v"(hi)); return r; }
;     __device__ __forceinline__ void operator()(const f32x4 (&acc)[2][2][4][2], const Unit& u, int wr, int wc, int fr, int fq) const {
;     ...
;         if (u.pn < 16) {
;             const float qs = u.pn < 8 ? (0.125f * 1.44269504089f) : 1.0f;
;             const int j0 = 16 * (wc & 1) + 4 * fq;
; #pragma unroll
;             for (int ai = 0; ai < 2; ++ai)
; #pragma unroll
;                 for (int m = 0; m < 4; ++m) { const int row = row0 + ai * 128 + m * 16, t = row & 4095;
;                     const f32x4 c4 = *(const f32x4*)(cs + t * 32 + j0), s4 = *(const f32x4*)(sn + t * 32 + j0);
; #pragma unroll
;                     for (int bj = 0; bj < 2; ++bj) { const int hh = 2 * bj + (wc >> 1);
;                         const f32x4 x1 = acc[ai][bj][m][0], x2 = acc[ai][bj][m][1]; float o1[4], o2[4];
; #pragma unroll
;                         for (int i = 0; i < 4; ++i) { o1[i] = (x1[i] * c4[i] - x2[i] * s4[i]) * qs; o2[i] = (x2[i] * c4[i] + x1[i] * s4[i]) * qs; }
;                         u16* dst = QK + (size_t)row * 4096 + u.pn * 256 + 64 * hh + j0;
;                         u32x2 a, b; a[0] = cvt_pk_bf16(o1[0], o1[1]); a[1] = cvt_pk_bf16(o1[2], o1[3]); b[0] = cvt_pk_bf16(o2[0], o2[1]); b[1] = cvt_pk_bf16(o2[2], o2[3]);
;                         *(u32x2*)dst = a; *(u32x2*)(dst + 32) = b; } }
	v_mov_b32_e32 v44, v32
	v_mov_b32_e32 v45, v36
	v_pk_mul_f32 v[42:43], v[42:43], v[44:45]
	v_mov_b32_e32 v36, v33
	v_sub_f32_e32 v32, v42, v43
	v_mov_b32_e32 v42, v24
	v_mov_b32_e32 v43, v28
	v_pk_mul_f32 v[42:43], v[42:43], v[44:45]
	v_mul_f32_e32 v46, v160, v32
	v_add_f32_e32 v24, v42, v43
	v_mul_f32_e32 v42, v160, v24
	v_mov_b32_e32 v24, v29
	v_pk_mul_f32 v[32:33], v[24:25], v[36:37]
	v_mov_b32_e32 v28, v25
	v_sub_f32_e32 v24, v32, v33
	v_mul_f32_e32 v32, v160, v24
	v_pk_mul_f32 v[24:25], v[28:29], v[36:37]
	v_mov_b32_e32 v28, v34
	v_add_f32_e32 v24, v24, v25
	v_mul_f32_e32 v33, v160, v24
	v_mov_b32_e32 v24, v30
	v_mov_b32_e32 v25, v26
	v_mov_b32_e32 v29, v38
	v_pk_mul_f32 v[24:25], v[24:25], v[28:29]
	v_mov_b32_e32 v38, v35
	v_sub_f32_e32 v24, v24, v25
	v_mul_f32_e32 v34, v160, v24
	v_mov_b32_e32 v24, v26
	v_mov_b32_e32 v25, v30
	v_pk_mul_f32 v[24:25], v[24:25], v[28:29]
	v_mov_b32_e32 v26, v31
	v_add_f32_e32 v24, v24, v25
	v_mul_f32_e32 v43, v160, v24
	v_pk_mul_f32 v[24:25], v[26:27], v[38:39]
	v_mov_b32_e32 v30, v27
	v_sub_f32_e32 v24, v24, v25
	v_mul_f32_e32 v35, v160, v24
	v_pk_mul_f32 v[24:25], v[30:31], v[38:39]
	v_cvt_pk_bf16_f32 v26, v46, v32
	v_cvt_pk_bf16_f32 v27, v34, v35
	v_cvt_pk_bf16_f32 v30, v42, v33
	s_nop 0
	v_add_f32_e32 v24, v24, v25
	v_mul_f32_e32 v31, v160, v24
	v_lshl_add_u64 v[24:25], s[96:97], 0, v[40:41]
	v_lshl_add_u64 v[24:25], v[24:25], 0, s[30:31]
	v_lshl_add_u64 v[24:25], v[24:25], 0, s[6:7]
	v_lshl_add_u64 v[24:25], v[24:25], 0, v[238:239]
	v_cvt_pk_bf16_f32 v31, v43, v31
	global_store_dwordx2 v[24:25], v[26:27], off
	global_store_dwordx2 v[24:25], v[30:31], off offset:64
	v_mov_b32_e32 v26, v20
	v_mov_b32_e32 v27, v16
	v_pk_mul_f32 v[26:27], v[26:27], v[44:45]
	s_nop 0
	v_sub_f32_e32 v26, v26, v27
	v_mul_f32_e32 v30, v160, v26
	v_mov_b32_e32 v26, v16
	v_mov_b32_e32 v27, v20
	v_pk_mul_f32 v[26:27], v[26:27], v[44:45]
	v_mov_b32_e32 v20, v17
	v_add_f32_e32 v16, v26, v27
	v_mul_f32_e32 v31, v160, v16
	v_mov_b32_e32 v16, v21
	v_pk_mul_f32 v[26:27], v[16:17], v[36:37]
	s_nop 0
	v_sub_f32_e32 v16, v26, v27
	v_mul_f32_e32 v26, v160, v16
	v_pk_mul_f32 v[16:17], v[20:21], v[36:37]
	s_nop 0
	v_add_f32_e32 v16, v16, v17
	v_mul_f32_e32 v20, v160, v16
	v_mov_b32_e32 v16, v22
	v_mov_b32_e32 v17, v18
	v_pk_mul_f32 v[16:17], v[16:17], v[28:29]
	s_nop 0
	v_sub_f32_e32 v16, v16, v17
	v_mul_f32_e32 v21, v160, v16
	v_mov_b32_e32 v16, v18
	v_mov_b32_e32 v17, v22
	v_pk_mul_f32 v[16:17], v[16:17], v[28:29]
	v_mov_b32_e32 v18, v23
	v_add_f32_e32 v16, v16, v17
	v_mul_f32_e32 v27, v160, v16
	v_pk_mul_f32 v[16:17], v[18:19], v[38:39]
	v_mov_b32_e32 v22, v19
	v_sub_f32_e32 v16, v16, v17
	v_mul_f32_e32 v18, v160, v16
	v_pk_mul_f32 v[16:17], v[22:23], v[38:39]
	s_nop 0
	v_add_f32_e32 v16, v16, v17
	v_mul_f32_e32 v19, v160, v16
	v_cvt_pk_bf16_f32 v16, v30, v26
	v_cvt_pk_bf16_f32 v17, v21, v18
	v_cvt_pk_bf16_f32 v18, v31, v20
	v_cvt_pk_bf16_f32 v19, v27, v19
	global_store_dwordx2 v[24:25], v[16:17], off offset:256
	global_store_dwordx2 v[24:25], v[18:19], off offset:320
	v_add_u32_e32 v24, 0xb0, v148
	v_lshlrev_b32_e32 v16, 7, v24
	v_and_b32_e32 v132, 0x7ff80, v16
	v_lshl_add_u64 v[16:17], v[134:135], 0, v[132:133]
	v_lshl_add_u64 v[20:21], v[136:137], 0, v[132:133]
	global_load_dwordx4 v[16:19], v[16:17], off
	s_nop 0
	global_load_dwordx4 v[20:23], v[20:21], off
	v_mov_b32_e32 v26, v12
	v_mov_b32_e32 v27, v8
	v_ashrrev_i32_e32 v25, 31, v24
	v_lshlrev_b64 v[24:25], 13, v[24:25]
	s_waitcnt vmcnt(0)
	v_mov_b32_e32 v28, v16
	v_mov_b32_e32 v29, v20
	v_pk_mul_f32 v[26:27], v[26:27], v[28:29]
	v_mov_b32_e32 v20, v17
	v_sub_f32_e32 v16, v26, v27
	v_mov_b32_e32 v26, v8
	v_mov_b32_e32 v27, v12
	v_pk_mul_f32 v[26:27], v[26:27], v[28:29]
	v_mul_f32_e32 v30, v160, v16
	v_add_f32_e32 v8, v26, v27
	v_mul_f32_e32 v26, v160, v8
	v_mov_b32_e32 v8, v13
	v_pk_mul_f32 v[16:17], v[8:9], v[20:21]
	v_mov_b32_e32 v12, v9
	v_sub_f32_e32 v8, v16, v17
	v_mul_f32_e32 v16, v160, v8
	v_pk_mul_f32 v[8:9], v[12:13], v[20:21]
	v_mov_b32_e32 v12, v18
	v_add_f32_e32 v8, v8, v9
	v_mul_f32_e32 v17, v160, v8
	v_mov_b32_e32 v8, v14
	v_mov_b32_e32 v9, v10
	v_mov_b32_e32 v13, v22
	v_pk_mul_f32 v[8:9], v[8:9], v[12:13]
	v_mov_b32_e32 v22, v19
	v_sub_f32_e32 v8, v8, v9
	v_mul_f32_e32 v18, v160, v8
	v_mov_b32_e32 v8, v10
	v_mov_b32_e32 v9, v14
	v_pk_mul_f32 v[8:9], v[8:9], v[12:13]
	v_mov_b32_e32 v10, v15
	v_add_f32_e32 v8, v8, v9
	v_mul_f32_e32 v27, v160, v8
	v_pk_mul_f32 v[8:9], v[10:11], v[22:23]
	v_mov_b32_e32 v14, v11
	v_sub_f32_e32 v8, v8, v9
	v_mul_f32_e32 v19, v160, v8
	v_pk_mul_f32 v[8:9], v[14:15], v[22:23]
	v_cvt_pk_bf16_f32 v10, v30, v16
	v_cvt_pk_bf16_f32 v11, v18, v19
	v_cvt_pk_bf16_f32 v14, v26, v17
	s_nop 0
	v_add_f32_e32 v8, v8, v9
	v_mul_f32_e32 v15, v160, v8
	v_lshl_add_u64 v[8:9], s[96:97], 0, v[24:25]
	v_lshl_add_u64 v[8:9], v[8:9], 0, s[30:31]
	v_lshl_add_u64 v[8:9], v[8:9], 0, s[6:7]
	v_lshl_add_u64 v[8:9], v[8:9], 0, v[238:239]
	v_cvt_pk_bf16_f32 v15, v27, v15
	global_store_dwordx2 v[8:9], v[10:11], off
	global_store_dwordx2 v[8:9], v[14:15], off offset:64
	v_mov_b32_e32 v10, v4
	v_mov_b32_e32 v11, v0
	v_pk_mul_f32 v[10:11], v[10:11], v[28:29]
	s_nop 0
	v_sub_f32_e32 v10, v10, v11
	v_mul_f32_e32 v14, v160, v10
	v_mov_b32_e32 v10, v0
	v_mov_b32_e32 v11, v4
	v_pk_mul_f32 v[10:11], v[10:11], v[28:29]
	v_mov_b32_e32 v4, v1
	v_add_f32_e32 v0, v10, v11
	v_mul_f32_e32 v15, v160, v0
	v_mov_b32_e32 v0, v5
	v_pk_mul_f32 v[10:11], v[0:1], v[20:21]
	s_nop 0
	v_sub_f32_e32 v0, v10, v11
	v_mul_f32_e32 v10, v160, v0
	v_pk_mul_f32 v[0:1], v[4:5], v[20:21]
	s_nop 0
	v_add_f32_e32 v0, v0, v1
	v_mul_f32_e32 v4, v160, v0
	v_mov_b32_e32 v0, v6
	v_mov_b32_e32 v1, v2
	v_pk_mul_f32 v[0:1], v[0:1], v[12:13]
	s_nop 0
	v_sub_f32_e32 v0, v0, v1
	v_mul_f32_e32 v5, v160, v0
	v_mov_b32_e32 v0, v2
	v_mov_b32_e32 v1, v6
	v_pk_mul_f32 v[0:1], v[0:1], v[12:13]
	v_mov_b32_e32 v2, v7
	v_add_f32_e32 v0, v0, v1
	v_mul_f32_e32 v11, v160, v0
	v_pk_mul_f32 v[0:1], v[2:3], v[22:23]
	v_mov_b32_e32 v6, v3
	v_sub_f32_e32 v0, v0, v1
	v_mul_f32_e32 v2, v160, v0
	v_pk_mul_f32 v[0:1], v[6:7], v[22:23]
	s_nop 0
	v_add_f32_e32 v0, v0, v1
	v_mul_f32_e32 v3, v160, v0
	v_cvt_pk_bf16_f32 v0, v14, v10
	v_cvt_pk_bf16_f32 v1, v5, v2
	v_cvt_pk_bf16_f32 v2, v15, v4
	v_cvt_pk_bf16_f32 v3, v11, v3
	global_store_dwordx2 v[8:9], v[0:1], off offset:256
	global_store_dwordx2 v[8:9], v[2:3], off offset:320
	s_branch .LBB0_1953

; #define AT_LOADK(kt) do { _Pragma("unroll") for (int i_ = 0; i_ < 2; ++i_) { const int id_ = tid + 512 * i_; \
;             kr[i_] = *(const u32x4*)(kbase + (size_t)((kt) * 64 + (id_ >> 4)) * 4096 + (id_ & 15) * 8); } } while (0)
; #define AT_LOADV(kt) do { _Pragma("unroll") for (int i_ = 0; i_ < 2; ++i_) { const int id_ = tid + 512 * i_; \
;             vr[i_] = *(const u32x4*)(vbase + (size_t)(id_ >> 3) * 4096 + (kt) * 64 + (id_ & 7) * 8); } } while (0)
; __device__ __forceinline__ void phase_attn(const Params& p, unsigned char* lds) {
;     ...
;     for (int unit = blockIdx.x; unit < 2048; unit += gridDim.x) {
;         int qb = unit & 31, bh = unit >> 5;
;         if (gridDim.x == 256) { bh = (unit >> 8) * 8 + (blockIdx.x & 7); qb = blockIdx.x >> 3; }
;         const int h = bh & 15, b = bh >> 4;
;         const size_t qrow = (size_t)b * 4096 + 128 * qb + 32 * qsub + ql;
;         bf16x8 Qr[4];
; #pragma unroll
;         for (int ks = 0; ks < 4; ++ks) Qr[ks] = *(const bf16x8*)(QK + qrow * 4096 + 128 * h + 64 * cmap + 16 * ks + 8 * g);
;         f32x16 ot[4];
; #pragma unroll
;         for (int vb = 0; vb < 4; ++vb)
; #pragma unroll
;             for (int i = 0; i < 16; ++i) ot[vb][i] = 0.f;
;         float mrun = -1e30f, lsum = 0.f;
;         const u16* kbase = QK + (size_t)b * 4096 * 4096 + 2048 + 128 * h;
;         const u16* vbase = VT + (size_t)(b * 16 + h) * 128 * 4096;
;         u32x4 kr[2], vr[2];
;     ...
;         const int toff = 2 * qb;
;         AT_LOADK(toff & 63); AT_LOADV(toff & 63); AT_STOREK(0); AT_STOREV(0);
;         __syncthreads();
;     ...
;             AT_QK(st, buf);
;             float mloc = st[0][0];
; #pragma unroll
;             for (int i = 0; i < 16; ++i) { mloc = fmaxf(mloc, st[0][i]); mloc = fmaxf(mloc, st[1][i]); }
;             mloc = fmaxf(mloc, __shfl_xor(mloc, 32));
;             const float mnew = fmaxf(mrun, mloc);
;             if (__builtin_amdgcn_ballot_w64(mnew > mrun) != 0ull) {
;                 const float alpha = __builtin_amdgcn_exp2f(mrun - mnew);
;                 lsum *= alpha;
; #pragma unroll
;                 for (int vb = 0; vb < 4; ++vb)
; #pragma unroll
;                     for (int i = 0; i < 16; ++i) ot[vb][i] *= alpha;
;             }
;             mrun = mnew;
.LBB0_2020:
	s_ashr_i32 s30, s27, 5
	s_and_b32 s20, s30, -8
	s_and_b32 s12, s27, 31
	s_or_b32 s31, s20, s2
	s_and_b64 s[20:21], s[14:15], exec
	s_cselect_b32 s20, s31, s30
	s_cselect_b32 s12, s3, s12
	s_ashr_i32 s34, s20, 4
	s_ashr_i32 s35, s34, 31
	s_lshl_b64 s[30:31], s[34:35], 12
	s_lshl_b32 s36, s12, 7
	s_add_u32 s12, s30, s36
	s_addc_u32 s21, s31, 0
	v_or_b32_e32 v150, s12, v130
	s_lshl_b32 s12, s20, 7
	s_and_b32 s30, s12, 0x780
	s_lshl_b32 s12, s30, 1
	s_lshl_b64 s[34:35], s[34:35], 25
	v_mov_b32_e32 v151, s21
	s_add_u32 s21, s96, s34
	s_addc_u32 s31, s97, s35
	v_lshlrev_b64 v[0:1], 13, v[150:151]
	s_add_u32 s34, s21, s12
	v_lshl_add_u64 v[0:1], s[96:97], 0, v[0:1]
	s_addc_u32 s35, s31, 0
	s_ashr_i32 s21, s20, 31
	v_mov_b32_e32 v145, v133
	v_lshl_add_u64 v[0:1], v[0:1], 0, s[12:13]
	s_lshl_b64 s[20:21], s[20:21], 20
	s_and_b32 s12, s36, 0xf80
	v_lshl_add_u64 v[2:3], s[34:35], 0, v[144:145]
	v_lshl_add_u64 v[152:153], v[2:3], 0, s[16:17]
	s_lshr_b32 s31, s30, 8
	v_and_b32_e32 v4, 7, v162
	v_add_u32_e32 v4, s31, v4
	v_and_b32_e32 v4, 7, v4
	v_subrev_u32_e32 v4, s31, v4
	v_lshlrev_b32_e32 v4, 9, v4
	v_ashrrev_i32_e32 v5, 31, v4
	v_lshl_add_u64 v[152:153], v[152:153], 0, v[4:5]
	v_add_u32_e32 v2, s12, v162
	s_add_u32 s34, s0, s20
	v_ashrrev_i32_e32 v3, 31, v2
	v_add_u32_e32 v4, s12, v163
	s_addc_u32 s35, s1, s21
	s_lshl_b32 s12, s12, 1
	v_lshlrev_b64 v[2:3], 13, v[2:3]
	v_ashrrev_i32_e32 v5, 31, v4
	s_add_u32 s20, s34, s12
	v_lshl_add_u64 v[2:3], v[152:153], 0, v[2:3]
	v_lshlrev_b64 v[4:5], 13, v[4:5]
	s_addc_u32 s21, s35, 0
	v_mov_b32_e32 v147, v133
	v_lshl_add_u64 v[0:1], v[134:135], 1, v[0:1]
	v_lshl_add_u64 v[4:5], v[152:153], 0, v[4:5]
	global_load_dwordx4 v[64:67], v[2:3], off
	global_load_dwordx4 v[68:71], v[4:5], off
	v_lshl_add_u64 v[2:3], s[20:21], 0, v[146:147]
	v_lshl_add_u64 v[4:5], v[2:3], 0, v[136:137]
	v_lshl_add_u64 v[0:1], v[0:1], 0, v[132:133]
	v_lshl_add_u64 v[2:3], v[2:3], 0, v[138:139]
	global_load_dwordx4 v[72:75], v[4:5], off
	global_load_dwordx4 v[76:79], v[2:3], off
	v_and_b32_e32 v4, 7, v170
	v_add_u32_e32 v4, s31, v4
	v_and_b32_e32 v4, 7, v4
	v_subrev_u32_e32 v4, s31, v4
	v_lshlrev_b32_e32 v4, 9, v4
	v_ashrrev_i32_e32 v5, 31, v4
	v_lshl_add_u64 v[0:1], v[0:1], 0, v[4:5]
	global_load_dwordx4 v[108:111], v[0:1], off
	global_load_dwordx4 v[104:107], v[0:1], off offset:32
	global_load_dwordx4 v[100:103], v[0:1], off offset:64
	global_load_dwordx4 v[96:99], v[0:1], off offset:96
	v_mov_b32_e32 v14, v133
	v_mov_b32_e32 v15, v133
	v_mov_b32_e32 v0, v133
	v_mov_b32_e32 v1, v133
	v_mov_b32_e32 v2, v133
	v_mov_b32_e32 v3, v133
	v_mov_b32_e32 v4, v133
	v_mov_b32_e32 v5, v133
	v_mov_b32_e32 v6, v133
	v_mov_b32_e32 v7, v133
	v_mov_b32_e32 v8, v133
	v_mov_b32_e32 v9, v133
	v_mov_b32_e32 v10, v133
	v_mov_b32_e32 v11, v133
	v_mov_b32_e32 v12, v133
	v_mov_b32_e32 v13, v133
	v_mov_b64_e32 v[30:31], v[14:15]
	v_mov_b64_e32 v[46:47], v[14:15]
	v_mov_b64_e32 v[62:63], v[14:15]
	v_add_u32_e32 v80, v131, v164
	s_mov_b32 s20, 0
	v_mov_b32_e32 v149, 0xf149f2ca
	v_mov_b64_e32 v[28:29], v[12:13]
	v_mov_b64_e32 v[26:27], v[10:11]
	v_mov_b64_e32 v[24:25], v[8:9]
	v_mov_b64_e32 v[22:23], v[6:7]
	v_mov_b64_e32 v[20:21], v[4:5]
	v_mov_b64_e32 v[18:19], v[2:3]
	v_mov_b64_e32 v[16:17], v[0:1]
	v_mov_b64_e32 v[44:45], v[12:13]
	v_mov_b64_e32 v[42:43], v[10:11]
	v_mov_b64_e32 v[40:41], v[8:9]
	v_mov_b64_e32 v[38:39], v[6:7]
	v_mov_b64_e32 v[36:37], v[4:5]
	v_mov_b64_e32 v[34:35], v[2:3]
	v_mov_b64_e32 v[32:33], v[0:1]
	v_mov_b64_e32 v[60:61], v[12:13]
	v_mov_b64_e32 v[58:59], v[10:11]
	v_mov_b64_e32 v[56:57], v[8:9]
	v_mov_b64_e32 v[54:55], v[6:7]
	v_mov_b64_e32 v[52:53], v[4:5]
	v_mov_b64_e32 v[50:51], v[2:3]
	v_mov_b64_e32 v[48:49], v[0:1]
	v_lshl_add_u64 v[154:155], s[34:35], 0, v[146:147]
	s_or_b32 s21, s36, 64
	v_mov_b32_e32 v128, 0
	v_add_u32_e32 v81, v131, v165
	v_add_u32_e32 v82, v156, v166
	v_add_u32_e32 v83, v156, v167
	s_waitcnt vmcnt(7)
	ds_write_b128 v80, v[64:67]
	s_waitcnt vmcnt(6)
	ds_write_b128 v81, v[68:71]
	s_waitcnt vmcnt(5)
	ds_write_b128 v82, v[72:75] offset:34816
	s_waitcnt vmcnt(4)
	ds_write_b128 v83, v[76:79] offset:34816
	s_waitcnt lgkmcnt(0)
	s_barrier
.LBB0_2021:
	v_add_u32_e32 v147, 0x4800, v159
	s_and_b32 s12, s21, 0xfc0
	v_add_u32_e32 v116, s12, v162
	v_ashrrev_i32_e32 v117, 31, v116
	v_add_u32_e32 v112, s12, v163
	v_lshlrev_b64 v[116:117], 13, v[116:117]
	v_ashrrev_i32_e32 v113, 31, v112
	v_lshl_add_u64 v[116:117], v[152:153], 0, v[116:117]
	v_lshlrev_b64 v[112:113], 13, v[112:113]
	v_lshl_add_u64 v[112:113], v[152:153], 0, v[112:113]
	global_load_dwordx4 v[116:119], v[116:117], off
	global_load_dwordx4 v[112:115], v[112:113], off
	ds_read_b128 v[172:175], v157 offset:0
	ds_read_b128 v[176:179], v157 offset:32
	ds_read_b128 v[180:183], v157 offset:64
	ds_read_b128 v[184:187], v157 offset:96
	ds_read_b128 v[188:191], v157 offset:8704
	ds_read_b128 v[192:195], v157 offset:8736
	ds_read_b128 v[228:231], v157 offset:8768
	ds_read_b128 v[232:235], v157 offset:8800
	s_waitcnt vmcnt(2)
	s_waitcnt lgkmcnt(7)
	v_mfma_f32_32x32x16_bf16 v[80:95], v[172:175], v[108:111], 0
	s_waitcnt lgkmcnt(6)
	v_mfma_f32_32x32x16_bf16 v[80:95], v[176:179], v[104:107], v[80:95]
	s_waitcnt lgkmcnt(5)
	v_mfma_f32_32x32x16_bf16 v[80:95], v[180:183], v[100:103], v[80:95]
	s_waitcnt lgkmcnt(4)
	v_mfma_f32_32x32x16_bf16 v[80:95], v[184:187], v[96:99], v[80:95]
	s_waitcnt lgkmcnt(3)
	v_mfma_f32_32x32x16_bf16 v[64:79], v[188:191], v[108:111], 0
	s_waitcnt lgkmcnt(2)
	v_mfma_f32_32x32x16_bf16 v[64:79], v[192:195], v[104:107], v[64:79]
	s_waitcnt lgkmcnt(1)
	v_mfma_f32_32x32x16_bf16 v[64:79], v[228:231], v[100:103], v[64:79]
	s_waitcnt lgkmcnt(0)
	v_mfma_f32_32x32x16_bf16 v[64:79], v[232:235], v[96:99], v[64:79]
	v_add_u32_e32 v239, v131, v164
	s_waitcnt vmcnt(1)
	ds_write_b128 v239, v[116:119] offset:17408
	v_add_u32_e32 v239, v131, v165
	s_waitcnt vmcnt(0)
	ds_write_b128 v239, v[112:115] offset:17408
	s_nop 7
	s_nop 3
	v_max3_f32 v145, v80, v81, v82
	v_max3_f32 v237, v64, v65, v66
	v_max3_f32 v145, v145, v83, v84
	v_max3_f32 v237, v237, v67, v68
	v_max3_f32 v145, v145, v85, v86
	v_max3_f32 v237, v237, v69, v70
	v_max3_f32 v145, v145, v87, v88
	v_max3_f32 v237, v237, v71, v72
	v_max3_f32 v145, v145, v89, v90
	v_max3_f32 v237, v237, v73, v74
	v_max3_f32 v145, v145, v91, v92
	v_max3_f32 v237, v237, v75, v76
	v_max3_f32 v145, v145, v93, v94
	v_max3_f32 v237, v237, v77, v78
	v_max_f32_e32 v145, v145, v95
	v_max_f32_e32 v237, v237, v79
	v_max_f32_e32 v145, v145, v237
	ds_bpermute_b32 v237, v158, v145
	s_waitcnt lgkmcnt(0)
	v_max3_f32 v145, v149, v145, v237
	v_sub_f32_e32 v238, v149, v145
	v_cmp_gt_f32_e32 vcc, v145, v149
	v_exp_f32_e32 v238, v238
	v_mov_b32_e32 v149, v145
	s_barrier
; __device__ __forceinline__ unsigned cvt_pk_bf16(float lo, float hi) { unsigned r; asm volatile("v_cvt_pk_bf16_f32 %0, %1, %2" : "=v"(r) : "v"(lo), "v"(hi)); return r; }
; #define AT_LOADK(kt) do { _Pragma("unroll") for (int i_ = 0; i_ < 2; ++i_) { const int id_ = tid + 512 * i_; \
;             kr[i_] = *(const u32x4*)(kbase + (size_t)((kt) * 64 + (id_ >> 4)) * 4096 + (id_ & 15) * 8); } } while (0)
; #define AT_LOADV(kt) do { _Pragma("unroll") for (int i_ = 0; i_ < 2; ++i_) { const int id_ = tid + 512 * i_; \
;             vr[i_] = *(const u32x4*)(vbase + (size_t)(id_ >> 3) * 4096 + (kt) * 64 + (id_ & 7) * 8); } } while (0)
; __device__ __forceinline__ void phase_attn(const Params& p, unsigned char* lds) {
;     ...
;             if (kt + 1 < 64) { AT_LOADK((kt + 1 + toff) & 63); AT_LOADV((kt + 1 + toff) & 63); }
;             AT_QK(st, buf);
;             float mloc = st[0][0];
; #pragma unroll
;             for (int i = 0; i < 16; ++i) { mloc = fmaxf(mloc, st[0][i]); mloc = fmaxf(mloc, st[1][i]); }
;             mloc = fmaxf(mloc, __shfl_xor(mloc, 32));
;             const float mnew = fmaxf(mrun, mloc);
;             if (__builtin_amdgcn_ballot_w64(mnew > mrun) != 0ull) {
;                 const float alpha = __builtin_amdgcn_exp2f(mrun - mnew);
;                 lsum *= alpha;
; #pragma unroll
;                 for (int vb = 0; vb < 4; ++vb)
; #pragma unroll
;                     for (int i = 0; i < 16; ++i) ot[vb][i] *= alpha;
;             }
;             mrun = mnew;
;             bf16x8 P[2][2];
; #pragma unroll
;             for (int kb = 0; kb < 2; ++kb)
; #pragma unroll
;                 for (int s2 = 0; s2 < 2; ++s2) { u32x4 pk;
; #pragma unroll
;                     for (int jj = 0; jj < 4; ++jj) { const float p0 = __builtin_amdgcn_exp2f(st[kb][8 * s2 + 2 * jj] - mnew), p1 = __builtin_amdgcn_exp2f(st[kb][8 * s2 + 2 * jj + 1] - mnew); lsum += p0 + p1; pk[jj] = cvt_pk_bf16(p0, p1); }
;                     P[kb][s2] = __builtin_bit_cast(bf16x8, pk); }
.Lat_loop:
	ds_read_b128 v[172:175], v157 offset:17408
	ds_read_b128 v[176:179], v157 offset:17440
	ds_read_b128 v[180:183], v157 offset:17472
	ds_read_b128 v[184:187], v157 offset:17504
	ds_read_b128 v[188:191], v157 offset:26112
	ds_read_b128 v[192:195], v157 offset:26144
	ds_read_b128 v[228:231], v157 offset:26176
	ds_read_b128 v[232:235], v157 offset:26208
	s_add_i32 s12, s21, 64
	s_and_b32 s12, s12, 0xfc0
	v_add_u32_e32 v116, s12, v162
	v_ashrrev_i32_e32 v117, 31, v116
	v_add_u32_e32 v112, s12, v163
	v_lshlrev_b64 v[116:117], 13, v[116:117]
	v_ashrrev_i32_e32 v113, 31, v112
	v_lshl_add_u64 v[116:117], v[152:153], 0, v[116:117]
	v_lshlrev_b64 v[112:113], 13, v[112:113]
	v_lshl_add_u64 v[112:113], v[152:153], 0, v[112:113]
	global_load_dwordx4 v[116:119], v[116:117], off
	global_load_dwordx4 v[112:115], v[112:113], off
	s_and_b32 s12, s21, 0xfc0
	s_lshl_b32 s12, s12, 1
	v_lshl_add_u64 v[124:125], v[154:155], 0, s[12:13]
	v_lshl_add_u64 v[120:121], v[124:125], 0, v[138:139]
	v_lshl_add_u64 v[124:125], v[124:125], 0, v[136:137]
	global_load_dwordx4 v[124:127], v[124:125], off
	global_load_dwordx4 v[120:123], v[120:121], off
	s_cbranch_vccz .Lat_norescale_1
	v_pk_mul_f32 v[0:1], v[0:1], v[238:239] op_sel_hi:[1,0]
	v_pk_mul_f32 v[2:3], v[2:3], v[238:239] op_sel_hi:[1,0]
	v_pk_mul_f32 v[4:5], v[4:5], v[238:239] op_sel_hi:[1,0]
	v_pk_mul_f32 v[6:7], v[6:7], v[238:239] op_sel_hi:[1,0]
	v_pk_mul_f32 v[8:9], v[8:9], v[238:239] op_sel_hi:[1,0]
	v_pk_mul_f32 v[10:11], v[10:11], v[238:239] op_sel_hi:[1,0]
	v_pk_mul_f32 v[12:13], v[12:13], v[238:239] op_sel_hi:[1,0]
	v_pk_mul_f32 v[14:15], v[14:15], v[238:239] op_sel_hi:[1,0]
	v_pk_mul_f32 v[16:17], v[16:17], v[238:239] op_sel_hi:[1,0]
	v_pk_mul_f32 v[18:19], v[18:19], v[238:239] op_sel_hi:[1,0]
	v_pk_mul_f32 v[20:21], v[20:21], v[238:239] op_sel_hi:[1,0]
	v_pk_mul_f32 v[22:23], v[22:23], v[238:239] op_sel_hi:[1,0]
	v_pk_mul_f32 v[24:25], v[24:25], v[238:239] op_sel_hi:[1,0]
	v_pk_mul_f32 v[26:27], v[26:27], v[238:239] op_sel_hi:[1,0]
	v_pk_mul_f32 v[28:29], v[28:29], v[238:239] op_sel_hi:[1,0]
	v_pk_mul_f32 v[30:31], v[30:31], v[238:239] op_sel_hi:[1,0]
	v_pk_mul_f32 v[32:33], v[32:33], v[238:239] op_sel_hi:[1,0]
	v_pk_mul_f32 v[34:35], v[34:35], v[238:239] op_sel_hi:[1,0]
	v_pk_mul_f32 v[36:37], v[36:37], v[238:239] op_sel_hi:[1,0]
	v_pk_mul_f32 v[38:39], v[38:39], v[238:239] op_sel_hi:[1,0]
	v_pk_mul_f32 v[40:41], v[40:41], v[238:239] op_sel_hi:[1,0]
	v_pk_mul_f32 v[42:43], v[42:43], v[238:239] op_sel_hi:[1,0]
	v_pk_mul_f32 v[44:45], v[44:45], v[238:239] op_sel_hi:[1,0]
	v_pk_mul_f32 v[46:47], v[46:47], v[238:239] op_sel_hi:[1,0]
	v_pk_mul_f32 v[48:49], v[48:49], v[238:239] op_sel_hi:[1,0]
	v_pk_mul_f32 v[50:51], v[50:51], v[238:239] op_sel_hi:[1,0]
	v_pk_mul_f32 v[52:53], v[52:53], v[238:239] op_sel_hi:[1,0]
	v_pk_mul_f32 v[54:55], v[54:55], v[238:239] op_sel_hi:[1,0]
	v_pk_mul_f32 v[56:57], v[56:57], v[238:239] op_sel_hi:[1,0]
	v_pk_mul_f32 v[58:59], v[58:59], v[238:239] op_sel_hi:[1,0]
	v_pk_mul_f32 v[60:61], v[60:61], v[238:239] op_sel_hi:[1,0]
	v_pk_mul_f32 v[62:63], v[62:63], v[238:239] op_sel_hi:[1,0]
	v_mul_f32_e32 v128, v128, v238
.Lat_norescale_1:
	v_mov_b32_e32 v236, 0
	s_waitcnt lgkmcnt(7)
	v_mfma_f32_32x32x16_bf16 v[196:211], v[172:175], v[108:111], 0
	v_sub_f32_e32 v80, v80, v149
	v_sub_f32_e32 v81, v81, v149
	v_sub_f32_e32 v82, v82, v149
	v_sub_f32_e32 v83, v83, v149
	v_exp_f32_e32 v80, v80
	v_exp_f32_e32 v81, v81
	v_exp_f32_e32 v82, v82
	v_exp_f32_e32 v83, v83
	v_add_f32_e32 v128, v128, v80
	v_add_f32_e32 v236, v236, v81
	v_cvt_pk_bf16_f32 v80, v80, v81
	v_add_f32_e32 v128, v128, v82
	v_add_f32_e32 v236, v236, v83
	v_cvt_pk_bf16_f32 v81, v82, v83
	s_waitcnt lgkmcnt(6)
	v_mfma_f32_32x32x16_bf16 v[196:211], v[176:179], v[104:107], v[196:211]
	v_sub_f32_e32 v84, v84, v149
	v_sub_f32_e32 v85, v85, v149
	v_sub_f32_e32 v86, v86, v149
	v_sub_f32_e32 v87, v87, v149
	v_exp_f32_e32 v84, v84
	v_exp_f32_e32 v85, v85
	v_exp_f32_e32 v86, v86
	v_exp_f32_e32 v87, v87
	v_add_f32_e32 v128, v128, v84
	v_add_f32_e32 v236, v236, v85
	v_cvt_pk_bf16_f32 v82, v84, v85
	v_add_f32_e32 v128, v128, v86
	v_add_f32_e32 v236, v236, v87
	v_cvt_pk_bf16_f32 v83, v86, v87
	s_waitcnt lgkmcnt(5)
	v_mfma_f32_32x32x16_bf16 v[196:211], v[180:183], v[100:103], v[196:211]
	v_sub_f32_e32 v88, v88, v149
	v_sub_f32_e32 v89, v89, v149
	v_sub_f32_e32 v90, v90, v149
	v_sub_f32_e32 v91, v91, v149
	v_exp_f32_e32 v88, v88
	v_exp_f32_e32 v89, v89
	v_exp_f32_e32 v90, v90
	v_exp_f32_e32 v91, v91
	v_add_f32_e32 v128, v128, v88
	v_add_f32_e32 v236, v236, v89
	v_cvt_pk_bf16_f32 v84, v88, v89
	v_add_f32_e32 v128, v128, v90
	v_add_f32_e32 v236, v236, v91
	v_cvt_pk_bf16_f32 v85, v90, v91
	s_waitcnt lgkmcnt(4)
	v_mfma_f32_32x32x16_bf16 v[196:211], v[184:187], v[96:99], v[196:211]
	ds_read_b128 v[172:175], v159 offset:34816
	ds_read_b128 v[176:179], v159 offset:34848
	ds_read_b128 v[180:183], v159 offset:34880
	ds_read_b128 v[184:187], v159 offset:34912
	v_sub_f32_e32 v92, v92, v149
	v_sub_f32_e32 v93, v93, v149
	v_sub_f32_e32 v94, v94, v149
	v_sub_f32_e32 v95, v95, v149
	v_exp_f32_e32 v92, v92
	v_exp_f32_e32 v93, v93
	v_exp_f32_e32 v94, v94
	v_exp_f32_e32 v95, v95
	v_add_f32_e32 v128, v128, v92
	v_add_f32_e32 v236, v236, v93
	v_cvt_pk_bf16_f32 v86, v92, v93
	v_add_f32_e32 v128, v128, v94
	v_add_f32_e32 v236, v236, v95
	v_cvt_pk_bf16_f32 v87, v94, v95
	s_waitcnt lgkmcnt(7)
	v_mfma_f32_32x32x16_bf16 v[212:227], v[188:191], v[108:111], 0
	v_sub_f32_e32 v64, v64, v149
	v_sub_f32_e32 v65, v65, v149
	v_sub_f32_e32 v66, v66, v149
	v_sub_f32_e32 v67, v67, v149
	v_exp_f32_e32 v64, v64
	v_exp_f32_e32 v65, v65
	v_exp_f32_e32 v66, v66
	v_exp_f32_e32 v67, v67
	v_add_f32_e32 v128, v128, v64
	v_add_f32_e32 v236, v236, v65
	v_cvt_pk_bf16_f32 v64, v64, v65
	v_add_f32_e32 v128, v128, v66
	v_add_f32_e32 v236, v236, v67
	v_cvt_pk_bf16_f32 v65, v66, v67
	s_waitcnt lgkmcnt(6)
; #define AT_STOREK(buf) do { _Pragma("unroll") for (int i_ = 0; i_ < 2; ++i_) { const int id_ = tid + 512 * i_; \
;             *(u32x4*)(sKt + (buf) * 8704 + (id_ >> 4) * 136 + (id_ & 15) * 8) = kr[i_]; } } while (0)
; #define AT_STOREV(buf) do { _Pragma("unroll") for (int i_ = 0; i_ < 2; ++i_) { const int id_ = tid + 512 * i_; \
;             *(u32x4*)(sVt + (buf) * 9216 + (id_ >> 3) * 72 + (id_ & 7) * 8) = vr[i_]; } } while (0)
; #define AT_LDV(set, vb) do { _Pragma("unroll") for (int kb = 0; kb < 2; ++kb) _Pragma("unroll") for (int s2 = 0; s2 < 2; ++s2) \
;                     vf[set][kb * 2 + s2] = *(const bf16x8*)(sVt + buf * 9216 + (32 * (vb) + ql) * 72 + 32 * kb + 16 * s2 + 8 * g); } while (0)
; __device__ __forceinline__ void phase_attn(const Params& p, unsigned char* lds) {
;     ...
;             AT_QK(st, buf);
;             float mloc = st[0][0];
; #pragma unroll
;             for (int i = 0; i < 16; ++i) { mloc = fmaxf(mloc, st[0][i]); mloc = fmaxf(mloc, st[1][i]); }
;             mloc = fmaxf(mloc, __shfl_xor(mloc, 32));
;             const float mnew = fmaxf(mrun, mloc);
;             if (__builtin_amdgcn_ballot_w64(mnew > mrun) != 0ull) {
;                 const float alpha = __builtin_amdgcn_exp2f(mrun - mnew);
;                 lsum *= alpha;
; #pragma unroll
;                 for (int vb = 0; vb < 4; ++vb)
; #pragma unroll
;                     for (int i = 0; i < 16; ++i) ot[vb][i] *= alpha;
;             }
;             mrun = mnew;
;     ...
;             {
;                 bf16x8 vf[2][4];
;     ...
;                 AT_LDV(0, 0);
; #pragma unroll
;                 for (int vb = 0; vb < 4; ++vb) {
;                     if (vb < 3) AT_LDV((vb + 1) & 1, vb + 1);
;                     __builtin_amdgcn_sched_barrier(0);
;                     __builtin_amdgcn_s_setprio(2);
; #pragma unroll
;                     for (int kb = 0; kb < 2; ++kb)
; #pragma unroll
;                         for (int s2 = 0; s2 < 2; ++s2) ot[vb] = __builtin_amdgcn_mfma_f32_32x32x16_bf16(vf[vb & 1][kb * 2 + s2], P[kb][s2], ot[vb], 0, 0, 0);
;                     __builtin_amdgcn_s_setprio(0);
;                     __builtin_amdgcn_sched_barrier(0);
;                 }
;     ...
;             }
;             if (kt + 1 < 64) { AT_STOREK(buf ^ 1); AT_STOREV(buf ^ 1); }
;             __syncthreads();
;         }
	v_mfma_f32_32x32x16_bf16 v[212:227], v[192:195], v[104:107], v[212:227]
	v_sub_f32_e32 v68, v68, v149
	v_sub_f32_e32 v69, v69, v149
	v_sub_f32_e32 v70, v70, v149
	v_sub_f32_e32 v71, v71, v149
	v_exp_f32_e32 v68, v68
	v_exp_f32_e32 v69, v69
	v_exp_f32_e32 v70, v70
	v_exp_f32_e32 v71, v71
	v_add_f32_e32 v128, v128, v68
	v_add_f32_e32 v236, v236, v69
	v_cvt_pk_bf16_f32 v66, v68, v69
	v_add_f32_e32 v128, v128, v70
	v_add_f32_e32 v236, v236, v71
	v_cvt_pk_bf16_f32 v67, v70, v71
	s_waitcnt lgkmcnt(5)
	v_mfma_f32_32x32x16_bf16 v[212:227], v[228:231], v[100:103], v[212:227]
	v_sub_f32_e32 v72, v72, v149
	v_sub_f32_e32 v73, v73, v149
	v_sub_f32_e32 v74, v74, v149
	v_sub_f32_e32 v75, v75, v149
	v_exp_f32_e32 v72, v72
	v_exp_f32_e32 v73, v73
	v_exp_f32_e32 v74, v74
	v_exp_f32_e32 v75, v75
	v_add_f32_e32 v128, v128, v72
	v_add_f32_e32 v236, v236, v73
	v_cvt_pk_bf16_f32 v68, v72, v73
	v_add_f32_e32 v128, v128, v74
	v_add_f32_e32 v236, v236, v75
	v_cvt_pk_bf16_f32 v69, v74, v75
	s_waitcnt lgkmcnt(4)
	v_mfma_f32_32x32x16_bf16 v[212:227], v[232:235], v[96:99], v[212:227]
	ds_read_b128 v[188:191], v159 offset:39424
	ds_read_b128 v[192:195], v159 offset:39456
	ds_read_b128 v[228:231], v159 offset:39488
	ds_read_b128 v[232:235], v159 offset:39520
	v_sub_f32_e32 v76, v76, v149
	v_sub_f32_e32 v77, v77, v149
	v_sub_f32_e32 v78, v78, v149
	v_sub_f32_e32 v79, v79, v149
	v_exp_f32_e32 v76, v76
	v_exp_f32_e32 v77, v77
	v_exp_f32_e32 v78, v78
	v_exp_f32_e32 v79, v79
	v_add_f32_e32 v128, v128, v76
	v_add_f32_e32 v236, v236, v77
	v_cvt_pk_bf16_f32 v70, v76, v77
	v_add_f32_e32 v128, v128, v78
	v_add_f32_e32 v236, v236, v79
	v_cvt_pk_bf16_f32 v71, v78, v79
	v_add_f32_e32 v128, v128, v236
	s_waitcnt lgkmcnt(7)
	v_mfma_f32_32x32x16_bf16 v[48:63], v[172:175], v[80:83], v[48:63]
	s_waitcnt lgkmcnt(6)
	v_mfma_f32_32x32x16_bf16 v[48:63], v[176:179], v[84:87], v[48:63]
	v_max3_f32 v145, v196, v197, v198
	v_max3_f32 v237, v212, v213, v214
	v_max3_f32 v145, v145, v199, v200
	s_waitcnt lgkmcnt(5)
	v_mfma_f32_32x32x16_bf16 v[48:63], v[180:183], v[64:67], v[48:63]
	v_max3_f32 v237, v237, v215, v216
	v_max3_f32 v145, v145, v201, v202
	v_max3_f32 v237, v237, v217, v218
	s_waitcnt lgkmcnt(4)
	v_mfma_f32_32x32x16_bf16 v[48:63], v[184:187], v[68:71], v[48:63]
	v_max3_f32 v145, v145, v203, v204
	v_max3_f32 v237, v237, v219, v220
	v_max3_f32 v145, v145, v205, v206
	ds_read_b128 v[172:175], v159 offset:44032
	ds_read_b128 v[176:179], v159 offset:44064
	ds_read_b128 v[180:183], v159 offset:44096
	ds_read_b128 v[184:187], v159 offset:44128
	s_waitcnt lgkmcnt(7)
	v_mfma_f32_32x32x16_bf16 v[32:47], v[188:191], v[80:83], v[32:47]
	v_max3_f32 v237, v237, v221, v222
	v_max3_f32 v145, v145, v207, v208
	v_max3_f32 v237, v237, v223, v224
	s_waitcnt lgkmcnt(6)
	v_mfma_f32_32x32x16_bf16 v[32:47], v[192:195], v[84:87], v[32:47]
	v_max3_f32 v145, v145, v209, v210
	v_max3_f32 v237, v237, v225, v226
	v_max_f32_e32 v145, v145, v211
	s_waitcnt lgkmcnt(5)
	v_mfma_f32_32x32x16_bf16 v[32:47], v[228:231], v[64:67], v[32:47]
	v_max_f32_e32 v237, v237, v227
	v_max_f32_e32 v145, v145, v237
	ds_bpermute_b32 v237, v158, v145
	s_waitcnt lgkmcnt(5)
	v_mfma_f32_32x32x16_bf16 v[32:47], v[232:235], v[68:71], v[32:47]
	v_add_u32_e32 v239, v131, v164
	s_waitcnt vmcnt(3)
	ds_write_b128 v239, v[116:119] offset:0
	ds_read_b128 v[188:191], v159 offset:48640
	ds_read_b128 v[192:195], v159 offset:48672
	ds_read_b128 v[228:231], v159 offset:48704
	ds_read_b128 v[232:235], v159 offset:48736
	s_waitcnt lgkmcnt(9)
	v_mfma_f32_32x32x16_bf16 v[16:31], v[172:175], v[80:83], v[16:31]
	v_add_u32_e32 v239, v131, v165
	s_waitcnt vmcnt(2)
	ds_write_b128 v239, v[112:115] offset:0
	s_waitcnt lgkmcnt(9)
	v_mfma_f32_32x32x16_bf16 v[16:31], v[176:179], v[84:87], v[16:31]
	v_add_u32_e32 v239, v156, v166
	s_waitcnt vmcnt(1)
	ds_write_b128 v239, v[124:127] offset:53248
	s_waitcnt lgkmcnt(9)
	v_mfma_f32_32x32x16_bf16 v[16:31], v[180:183], v[64:67], v[16:31]
	v_add_u32_e32 v239, v156, v167
	s_waitcnt vmcnt(0)
	ds_write_b128 v239, v[120:123] offset:53248
	s_waitcnt lgkmcnt(9)
	v_mfma_f32_32x32x16_bf16 v[16:31], v[184:187], v[68:71], v[16:31]
	s_waitcnt lgkmcnt(8)
	v_max3_f32 v145, v149, v145, v237
	v_sub_f32_e32 v238, v149, v145
	v_cmp_gt_f32_e32 vcc, v145, v149
	s_waitcnt lgkmcnt(6)
	v_mfma_f32_32x32x16_bf16 v[0:15], v[188:191], v[80:83], v[0:15]
	v_exp_f32_e32 v238, v238
	s_waitcnt lgkmcnt(5)
	v_mfma_f32_32x32x16_bf16 v[0:15], v[192:195], v[84:87], v[0:15]
	s_waitcnt lgkmcnt(4)
	v_mfma_f32_32x32x16_bf16 v[0:15], v[228:231], v[64:67], v[0:15]
	s_waitcnt lgkmcnt(3)
	v_mfma_f32_32x32x16_bf16 v[0:15], v[232:235], v[68:71], v[0:15]
	v_mov_b32_e32 v149, v145
	s_add_i32 s21, s21, 64
	s_add_i32 s20, s20, 1
	s_waitcnt lgkmcnt(0)
	s_barrier
	s_cmp_eq_u32 s20, 63
	s_cbranch_scc1 .Lat_last
	ds_read_b128 v[172:175], v157 offset:0
	ds_read_b128 v[176:179], v157 offset:32
	ds_read_b128 v[180:183], v157 offset:64
	ds_read_b128 v[184:187], v157 offset:96
	ds_read_b128 v[188:191], v157 offset:8704
	ds_read_b128 v[192:195], v157 offset:8736
	ds_read_b128 v[228:231], v157 offset:8768
	ds_read_b128 v[232:235], v157 offset:8800
	s_add_i32 s12, s21, 64
	s_and_b32 s12, s12, 0xfc0
	v_add_u32_e32 v116, s12, v162
	v_ashrrev_i32_e32 v117, 31, v116
	v_add_u32_e32 v112, s12, v163
	v_lshlrev_b64 v[116:117], 13, v[116:117]
	v_ashrrev_i32_e32 v113, 31, v112
	v_lshl_add_u64 v[116:117], v[152:153], 0, v[116:117]
	v_lshlrev_b64 v[112:113], 13, v[112:113]
	v_lshl_add_u64 v[112:113], v[152:153], 0, v[112:113]
	global_load_dwordx4 v[116:119], v[116:117], off
	global_load_dwordx4 v[112:115], v[112:113], off
	s_and_b32 s12, s21, 0xfc0
	s_lshl_b32 s12, s12, 1
	v_lshl_add_u64 v[124:125], v[154:155], 0, s[12:13]
	v_lshl_add_u64 v[120:121], v[124:125], 0, v[138:139]
	v_lshl_add_u64 v[124:125], v[124:125], 0, v[136:137]
	global_load_dwordx4 v[124:127], v[124:125], off
	global_load_dwordx4 v[120:123], v[120:121], off
	s_cbranch_vccz .Lat_norescale_2
; __device__ __forceinline__ unsigned cvt_pk_bf16(float lo, float hi) { unsigned r; asm volatile("v_cvt_pk_bf16_f32 %0, %1, %2" : "=v"(r) : "v"(lo), "v"(hi)); return r; }
; __device__ __forceinline__ void phase_attn(const Params& p, unsigned char* lds) {
;     ...
;             if (__builtin_amdgcn_ballot_w64(mnew > mrun) != 0ull) {
;                 const float alpha = __builtin_amdgcn_exp2f(mrun - mnew);
;                 lsum *= alpha;
; #pragma unroll
;                 for (int vb = 0; vb < 4; ++vb)
; #pragma unroll
;                     for (int i = 0; i < 16; ++i) ot[vb][i] *= alpha;
;             }
;             mrun = mnew;
;             bf16x8 P[2][2];
; #pragma unroll
;             for (int kb = 0; kb < 2; ++kb)
; #pragma unroll
;                 for (int s2 = 0; s2 < 2; ++s2) { u32x4 pk;
; #pragma unroll
;                     for (int jj = 0; jj < 4; ++jj) { const float p0 = __builtin_amdgcn_exp2f(st[kb][8 * s2 + 2 * jj] - mnew), p1 = __builtin_amdgcn_exp2f(st[kb][8 * s2 + 2 * jj + 1] - mnew); lsum += p0 + p1; pk[jj] = cvt_pk_bf16(p0, p1); }
;                     P[kb][s2] = __builtin_bit_cast(bf16x8, pk); }
	v_pk_mul_f32 v[0:1], v[0:1], v[238:239] op_sel_hi:[1,0]
	v_pk_mul_f32 v[2:3], v[2:3], v[238:239] op_sel_hi:[1,0]
	v_pk_mul_f32 v[4:5], v[4:5], v[238:239] op_sel_hi:[1,0]
	v_pk_mul_f32 v[6:7], v[6:7], v[238:239] op_sel_hi:[1,0]
	v_pk_mul_f32 v[8:9], v[8:9], v[238:239] op_sel_hi:[1,0]
	v_pk_mul_f32 v[10:11], v[10:11], v[238:239] op_sel_hi:[1,0]
	v_pk_mul_f32 v[12:13], v[12:13], v[238:239] op_sel_hi:[1,0]
	v_pk_mul_f32 v[14:15], v[14:15], v[238:239] op_sel_hi:[1,0]
	v_pk_mul_f32 v[16:17], v[16:17], v[238:239] op_sel_hi:[1,0]
	v_pk_mul_f32 v[18:19], v[18:19], v[238:239] op_sel_hi:[1,0]
	v_pk_mul_f32 v[20:21], v[20:21], v[238:239] op_sel_hi:[1,0]
	v_pk_mul_f32 v[22:23], v[22:23], v[238:239] op_sel_hi:[1,0]
	v_pk_mul_f32 v[24:25], v[24:25], v[238:239] op_sel_hi:[1,0]
	v_pk_mul_f32 v[26:27], v[26:27], v[238:239] op_sel_hi:[1,0]
	v_pk_mul_f32 v[28:29], v[28:29], v[238:239] op_sel_hi:[1,0]
	v_pk_mul_f32 v[30:31], v[30:31], v[238:239] op_sel_hi:[1,0]
	v_pk_mul_f32 v[32:33], v[32:33], v[238:239] op_sel_hi:[1,0]
	v_pk_mul_f32 v[34:35], v[34:35], v[238:239] op_sel_hi:[1,0]
	v_pk_mul_f32 v[36:37], v[36:37], v[238:239] op_sel_hi:[1,0]
	v_pk_mul_f32 v[38:39], v[38:39], v[238:239] op_sel_hi:[1,0]
	v_pk_mul_f32 v[40:41], v[40:41], v[238:239] op_sel_hi:[1,0]
	v_pk_mul_f32 v[42:43], v[42:43], v[238:239] op_sel_hi:[1,0]
	v_pk_mul_f32 v[44:45], v[44:45], v[238:239] op_sel_hi:[1,0]
	v_pk_mul_f32 v[46:47], v[46:47], v[238:239] op_sel_hi:[1,0]
	v_pk_mul_f32 v[48:49], v[48:49], v[238:239] op_sel_hi:[1,0]
	v_pk_mul_f32 v[50:51], v[50:51], v[238:239] op_sel_hi:[1,0]
	v_pk_mul_f32 v[52:53], v[52:53], v[238:239] op_sel_hi:[1,0]
	v_pk_mul_f32 v[54:55], v[54:55], v[238:239] op_sel_hi:[1,0]
	v_pk_mul_f32 v[56:57], v[56:57], v[238:239] op_sel_hi:[1,0]
	v_pk_mul_f32 v[58:59], v[58:59], v[238:239] op_sel_hi:[1,0]
	v_pk_mul_f32 v[60:61], v[60:61], v[238:239] op_sel_hi:[1,0]
	v_pk_mul_f32 v[62:63], v[62:63], v[238:239] op_sel_hi:[1,0]
	v_mul_f32_e32 v128, v128, v238
.Lat_norescale_2:
	v_mov_b32_e32 v236, 0
	s_waitcnt lgkmcnt(7)
	v_mfma_f32_32x32x16_bf16 v[80:95], v[172:175], v[108:111], 0
	v_sub_f32_e32 v196, v196, v149
	v_sub_f32_e32 v197, v197, v149
	v_sub_f32_e32 v198, v198, v149
	v_sub_f32_e32 v199, v199, v149
	v_exp_f32_e32 v196, v196
	v_exp_f32_e32 v197, v197
	v_exp_f32_e32 v198, v198
	v_exp_f32_e32 v199, v199
	v_add_f32_e32 v128, v128, v196
	v_add_f32_e32 v236, v236, v197
	v_cvt_pk_bf16_f32 v196, v196, v197
	v_add_f32_e32 v128, v128, v198
	v_add_f32_e32 v236, v236, v199
	v_cvt_pk_bf16_f32 v197, v198, v199
	s_waitcnt lgkmcnt(6)
	v_mfma_f32_32x32x16_bf16 v[80:95], v[176:179], v[104:107], v[80:95]
	v_sub_f32_e32 v200, v200, v149
	v_sub_f32_e32 v201, v201, v149
	v_sub_f32_e32 v202, v202, v149
	v_sub_f32_e32 v203, v203, v149
	v_exp_f32_e32 v200, v200
	v_exp_f32_e32 v201, v201
	v_exp_f32_e32 v202, v202
	v_exp_f32_e32 v203, v203
	v_add_f32_e32 v128, v128, v200
	v_add_f32_e32 v236, v236, v201
	v_cvt_pk_bf16_f32 v198, v200, v201
	v_add_f32_e32 v128, v128, v202
	v_add_f32_e32 v236, v236, v203
	v_cvt_pk_bf16_f32 v199, v202, v203
	s_waitcnt lgkmcnt(5)
	v_mfma_f32_32x32x16_bf16 v[80:95], v[180:183], v[100:103], v[80:95]
	v_sub_f32_e32 v204, v204, v149
	v_sub_f32_e32 v205, v205, v149
	v_sub_f32_e32 v206, v206, v149
	v_sub_f32_e32 v207, v207, v149
	v_exp_f32_e32 v204, v204
	v_exp_f32_e32 v205, v205
	v_exp_f32_e32 v206, v206
	v_exp_f32_e32 v207, v207
	v_add_f32_e32 v128, v128, v204
	v_add_f32_e32 v236, v236, v205
	v_cvt_pk_bf16_f32 v200, v204, v205
	v_add_f32_e32 v128, v128, v206
	v_add_f32_e32 v236, v236, v207
	v_cvt_pk_bf16_f32 v201, v206, v207
	s_waitcnt lgkmcnt(4)
	v_mfma_f32_32x32x16_bf16 v[80:95], v[184:187], v[96:99], v[80:95]
	ds_read_b128 v[172:175], v147 offset:34816
	ds_read_b128 v[176:179], v147 offset:34848
	ds_read_b128 v[180:183], v147 offset:34880
	ds_read_b128 v[184:187], v147 offset:34912
	v_sub_f32_e32 v208, v208, v149
	v_sub_f32_e32 v209, v209, v149
	v_sub_f32_e32 v210, v210, v149
	v_sub_f32_e32 v211, v211, v149
	v_exp_f32_e32 v208, v208
	v_exp_f32_e32 v209, v209
	v_exp_f32_e32 v210, v210
	v_exp_f32_e32 v211, v211
	v_add_f32_e32 v128, v128, v208
	v_add_f32_e32 v236, v236, v209
	v_cvt_pk_bf16_f32 v202, v208, v209
	v_add_f32_e32 v128, v128, v210
	v_add_f32_e32 v236, v236, v211
	v_cvt_pk_bf16_f32 v203, v210, v211
	s_waitcnt lgkmcnt(7)
	v_mfma_f32_32x32x16_bf16 v[64:79], v[188:191], v[108:111], 0
	v_sub_f32_e32 v212, v212, v149
	v_sub_f32_e32 v213, v213, v149
	v_sub_f32_e32 v214, v214, v149
	v_sub_f32_e32 v215, v215, v149
	v_exp_f32_e32 v212, v212
	v_exp_f32_e32 v213, v213
	v_exp_f32_e32 v214, v214
	v_exp_f32_e32 v215, v215
	v_add_f32_e32 v128, v128, v212
	v_add_f32_e32 v236, v236, v213
	v_cvt_pk_bf16_f32 v212, v212, v213
	v_add_f32_e32 v128, v128, v214
	v_add_f32_e32 v236, v236, v215
	v_cvt_pk_bf16_f32 v213, v214, v215
	s_waitcnt lgkmcnt(6)
	v_mfma_f32_32x32x16_bf16 v[64:79], v[192:195], v[104:107], v[64:79]
	v_sub_f32_e32 v216, v216, v149
	v_sub_f32_e32 v217, v217, v149
	v_sub_f32_e32 v218, v218, v149
	v_sub_f32_e32 v219, v219, v149
	v_exp_f32_e32 v216, v216
	v_exp_f32_e32 v217, v217
	v_exp_f32_e32 v218, v218
	v_exp_f32_e32 v219, v219
	v_add_f32_e32 v128, v128, v216
	v_add_f32_e32 v236, v236, v217
	v_cvt_pk_bf16_f32 v214, v216, v217
	v_add_f32_e32 v128, v128, v218
	v_add_f32_e32 v236, v236, v219
	v_cvt_pk_bf16_f32 v215, v218, v219
	s_waitcnt lgkmcnt(5)
	v_mfma_f32_32x32x16_bf16 v[64:79], v[228:231], v[100:103], v[64:79]
	v_sub_f32_e32 v220, v220, v149
	v_sub_f32_e32 v221, v221, v149
	v_sub_f32_e32 v222, v222, v149
	v_sub_f32_e32 v223, v223, v149
	v_exp_f32_e32 v220, v220
	v_exp_f32_e32 v221, v221
	v_exp_f32_e32 v222, v222
	v_exp_f32_e32 v223, v223
	v_add_f32_e32 v128, v128, v220
	v_add_f32_e32 v236, v236, v221
	v_cvt_pk_bf16_f32 v216, v220, v221
	v_add_f32_e32 v128, v128, v222
	v_add_f32_e32 v236, v236, v223
	v_cvt_pk_bf16_f32 v217, v222, v223
	s_waitcnt lgkmcnt(4)
; #define AT_STOREK(buf) do { _Pragma("unroll") for (int i_ = 0; i_ < 2; ++i_) { const int id_ = tid + 512 * i_; \
;             *(u32x4*)(sKt + (buf) * 8704 + (id_ >> 4) * 136 + (id_ & 15) * 8) = kr[i_]; } } while (0)
; #define AT_STOREV(buf) do { _Pragma("unroll") for (int i_ = 0; i_ < 2; ++i_) { const int id_ = tid + 512 * i_; \
;             *(u32x4*)(sVt + (buf) * 9216 + (id_ >> 3) * 72 + (id_ & 7) * 8) = vr[i_]; } } while (0)
; #define AT_LDV(set, vb) do { _Pragma("unroll") for (int kb = 0; kb < 2; ++kb) _Pragma("unroll") for (int s2 = 0; s2 < 2; ++s2) \
;                     vf[set][kb * 2 + s2] = *(const bf16x8*)(sVt + buf * 9216 + (32 * (vb) + ql) * 72 + 32 * kb + 16 * s2 + 8 * g); } while (0)
; __device__ __forceinline__ void phase_attn(const Params& p, unsigned char* lds) {
;     ...
;             AT_QK(st, buf);
;             float mloc = st[0][0];
; #pragma unroll
;             for (int i = 0; i < 16; ++i) { mloc = fmaxf(mloc, st[0][i]); mloc = fmaxf(mloc, st[1][i]); }
;             mloc = fmaxf(mloc, __shfl_xor(mloc, 32));
;             const float mnew = fmaxf(mrun, mloc);
;             if (__builtin_amdgcn_ballot_w64(mnew > mrun) != 0ull) {
;                 const float alpha = __builtin_amdgcn_exp2f(mrun - mnew);
;                 lsum *= alpha;
; #pragma unroll
;                 for (int vb = 0; vb < 4; ++vb)
; #pragma unroll
;                     for (int i = 0; i < 16; ++i) ot[vb][i] *= alpha;
;             }
;             mrun = mnew;
;     ...
;             {
;                 bf16x8 vf[2][4];
;     ...
;                 AT_LDV(0, 0);
; #pragma unroll
;                 for (int vb = 0; vb < 4; ++vb) {
;                     if (vb < 3) AT_LDV((vb + 1) & 1, vb + 1);
;                     __builtin_amdgcn_sched_barrier(0);
;                     __builtin_amdgcn_s_setprio(2);
; #pragma unroll
;                     for (int kb = 0; kb < 2; ++kb)
; #pragma unroll
;                         for (int s2 = 0; s2 < 2; ++s2) ot[vb] = __builtin_amdgcn_mfma_f32_32x32x16_bf16(vf[vb & 1][kb * 2 + s2], P[kb][s2], ot[vb], 0, 0, 0);
;                     __builtin_amdgcn_s_setprio(0);
;                     __builtin_amdgcn_sched_barrier(0);
;                 }
;     ...
;             }
;             if (kt + 1 < 64) { AT_STOREK(buf ^ 1); AT_STOREV(buf ^ 1); }
;             __syncthreads();
;         }
	v_mfma_f32_32x32x16_bf16 v[64:79], v[232:235], v[96:99], v[64:79]
	ds_read_b128 v[188:191], v147 offset:39424
	ds_read_b128 v[192:195], v147 offset:39456
	ds_read_b128 v[228:231], v147 offset:39488
	ds_read_b128 v[232:235], v147 offset:39520
	v_sub_f32_e32 v224, v224, v149
	v_sub_f32_e32 v225, v225, v149
	v_sub_f32_e32 v226, v226, v149
	v_sub_f32_e32 v227, v227, v149
	v_exp_f32_e32 v224, v224
	v_exp_f32_e32 v225, v225
	v_exp_f32_e32 v226, v226
	v_exp_f32_e32 v227, v227
	v_add_f32_e32 v128, v128, v224
	v_add_f32_e32 v236, v236, v225
	v_cvt_pk_bf16_f32 v218, v224, v225
	v_add_f32_e32 v128, v128, v226
	v_add_f32_e32 v236, v236, v227
	v_cvt_pk_bf16_f32 v219, v226, v227
	v_add_f32_e32 v128, v128, v236
	s_waitcnt lgkmcnt(7)
	v_mfma_f32_32x32x16_bf16 v[48:63], v[172:175], v[196:199], v[48:63]
	s_waitcnt lgkmcnt(6)
	v_mfma_f32_32x32x16_bf16 v[48:63], v[176:179], v[200:203], v[48:63]
	v_max3_f32 v145, v80, v81, v82
	v_max3_f32 v237, v64, v65, v66
	v_max3_f32 v145, v145, v83, v84
	s_waitcnt lgkmcnt(5)
	v_mfma_f32_32x32x16_bf16 v[48:63], v[180:183], v[212:215], v[48:63]
	v_max3_f32 v237, v237, v67, v68
	v_max3_f32 v145, v145, v85, v86
	v_max3_f32 v237, v237, v69, v70
	s_waitcnt lgkmcnt(4)
	v_mfma_f32_32x32x16_bf16 v[48:63], v[184:187], v[216:219], v[48:63]
	v_max3_f32 v145, v145, v87, v88
	v_max3_f32 v237, v237, v71, v72
	v_max3_f32 v145, v145, v89, v90
	ds_read_b128 v[172:175], v147 offset:44032
	ds_read_b128 v[176:179], v147 offset:44064
	ds_read_b128 v[180:183], v147 offset:44096
	ds_read_b128 v[184:187], v147 offset:44128
	s_waitcnt lgkmcnt(7)
	v_mfma_f32_32x32x16_bf16 v[32:47], v[188:191], v[196:199], v[32:47]
	v_max3_f32 v237, v237, v73, v74
	v_max3_f32 v145, v145, v91, v92
	v_max3_f32 v237, v237, v75, v76
	s_waitcnt lgkmcnt(6)
	v_mfma_f32_32x32x16_bf16 v[32:47], v[192:195], v[200:203], v[32:47]
	v_max3_f32 v145, v145, v93, v94
	v_max3_f32 v237, v237, v77, v78
	v_max_f32_e32 v145, v145, v95
	s_waitcnt lgkmcnt(5)
	v_mfma_f32_32x32x16_bf16 v[32:47], v[228:231], v[212:215], v[32:47]
	v_max_f32_e32 v237, v237, v79
	v_max_f32_e32 v145, v145, v237
	ds_bpermute_b32 v237, v158, v145
	s_waitcnt lgkmcnt(5)
	v_mfma_f32_32x32x16_bf16 v[32:47], v[232:235], v[216:219], v[32:47]
	v_add_u32_e32 v239, v131, v164
	s_waitcnt vmcnt(3)
	ds_write_b128 v239, v[116:119] offset:17408
	ds_read_b128 v[188:191], v147 offset:48640
	ds_read_b128 v[192:195], v147 offset:48672
	ds_read_b128 v[228:231], v147 offset:48704
	ds_read_b128 v[232:235], v147 offset:48736
	s_waitcnt lgkmcnt(9)
	v_mfma_f32_32x32x16_bf16 v[16:31], v[172:175], v[196:199], v[16:31]
	v_add_u32_e32 v239, v131, v165
	s_waitcnt vmcnt(2)
	ds_write_b128 v239, v[112:115] offset:17408
	s_waitcnt lgkmcnt(9)
	v_mfma_f32_32x32x16_bf16 v[16:31], v[176:179], v[200:203], v[16:31]
	v_add_u32_e32 v239, v156, v166
	s_waitcnt vmcnt(1)
	ds_write_b128 v239, v[124:127] offset:34816
	s_waitcnt lgkmcnt(9)
	v_mfma_f32_32x32x16_bf16 v[16:31], v[180:183], v[212:215], v[16:31]
	v_add_u32_e32 v239, v156, v167
	s_waitcnt vmcnt(0)
	ds_write_b128 v239, v[120:123] offset:34816
	s_waitcnt lgkmcnt(9)
	v_mfma_f32_32x32x16_bf16 v[16:31], v[184:187], v[216:219], v[16:31]
	s_waitcnt lgkmcnt(8)
	v_max3_f32 v145, v149, v145, v237
	v_sub_f32_e32 v238, v149, v145
	v_cmp_gt_f32_e32 vcc, v145, v149
	s_waitcnt lgkmcnt(6)
	v_mfma_f32_32x32x16_bf16 v[0:15], v[188:191], v[196:199], v[0:15]
	v_exp_f32_e32 v238, v238
	s_waitcnt lgkmcnt(5)
	v_mfma_f32_32x32x16_bf16 v[0:15], v[192:195], v[200:203], v[0:15]
	s_waitcnt lgkmcnt(4)
	v_mfma_f32_32x32x16_bf16 v[0:15], v[228:231], v[212:215], v[0:15]
	s_waitcnt lgkmcnt(3)
	v_mfma_f32_32x32x16_bf16 v[0:15], v[232:235], v[216:219], v[0:15]
	v_mov_b32_e32 v149, v145
	s_add_i32 s21, s21, 64
	s_add_i32 s20, s20, 1
	s_waitcnt lgkmcnt(0)
	s_barrier
	s_branch .Lat_loop
.Lat_last:
	s_cbranch_vccz .Lat_norescale_3
	v_pk_mul_f32 v[0:1], v[0:1], v[238:239] op_sel_hi:[1,0]
	v_pk_mul_f32 v[2:3], v[2:3], v[238:239] op_sel_hi:[1,0]
	v_pk_mul_f32 v[4:5], v[4:5], v[238:239] op_sel_hi:[1,0]
	v_pk_mul_f32 v[6:7], v[6:7], v[238:239] op_sel_hi:[1,0]
	v_pk_mul_f32 v[8:9], v[8:9], v[238:239] op_sel_hi:[1,0]
	v_pk_mul_f32 v[10:11], v[10:11], v[238:239] op_sel_hi:[1,0]
	v_pk_mul_f32 v[12:13], v[12:13], v[238:239] op_sel_hi:[1,0]
	v_pk_mul_f32 v[14:15], v[14:15], v[238:239] op_sel_hi:[1,0]
	v_pk_mul_f32 v[16:17], v[16:17], v[238:239] op_sel_hi:[1,0]
	v_pk_mul_f32 v[18:19], v[18:19], v[238:239] op_sel_hi:[1,0]
	v_pk_mul_f32 v[20:21], v[20:21], v[238:239] op_sel_hi:[1,0]
	v_pk_mul_f32 v[22:23], v[22:23], v[238:239] op_sel_hi:[1,0]
	v_pk_mul_f32 v[24:25], v[24:25], v[238:239] op_sel_hi:[1,0]
	v_pk_mul_f32 v[26:27], v[26:27], v[238:239] op_sel_hi:[1,0]
	v_pk_mul_f32 v[28:29], v[28:29], v[238:239] op_sel_hi:[1,0]
	v_pk_mul_f32 v[30:31], v[30:31], v[238:239] op_sel_hi:[1,0]
	v_pk_mul_f32 v[32:33], v[32:33], v[238:239] op_sel_hi:[1,0]
	v_pk_mul_f32 v[34:35], v[34:35], v[238:239] op_sel_hi:[1,0]
	v_pk_mul_f32 v[36:37], v[36:37], v[238:239] op_sel_hi:[1,0]
	v_pk_mul_f32 v[38:39], v[38:39], v[238:239] op_sel_hi:[1,0]
	v_pk_mul_f32 v[40:41], v[40:41], v[238:239] op_sel_hi:[1,0]
	v_pk_mul_f32 v[42:43], v[42:43], v[238:239] op_sel_hi:[1,0]
	v_pk_mul_f32 v[44:45], v[44:45], v[238:239] op_sel_hi:[1,0]
	v_pk_mul_f32 v[46:47], v[46:47], v[238:239] op_sel_hi:[1,0]
	v_pk_mul_f32 v[48:49], v[48:49], v[238:239] op_sel_hi:[1,0]
	v_pk_mul_f32 v[50:51], v[50:51], v[238:239] op_sel_hi:[1,0]
	v_pk_mul_f32 v[52:53], v[52:53], v[238:239] op_sel_hi:[1,0]
	v_pk_mul_f32 v[54:55], v[54:55], v[238:239] op_sel_hi:[1,0]
	v_pk_mul_f32 v[56:57], v[56:57], v[238:239] op_sel_hi:[1,0]
	v_pk_mul_f32 v[58:59], v[58:59], v[238:239] op_sel_hi:[1,0]
	v_pk_mul_f32 v[60:61], v[60:61], v[238:239] op_sel_hi:[1,0]
	v_pk_mul_f32 v[62:63], v[62:63], v[238:239] op_sel_hi:[1,0]
	v_mul_f32_e32 v128, v128, v238
; __device__ __forceinline__ unsigned cvt_pk_bf16(float lo, float hi) { unsigned r; asm volatile("v_cvt_pk_bf16_f32 %0, %1, %2" : "=v"(r) : "v"(lo), "v"(hi)); return r; }
; #define AT_LDV(set, vb) do { _Pragma("unroll") for (int kb = 0; kb < 2; ++kb) _Pragma("unroll") for (int s2 = 0; s2 < 2; ++s2) \
;                     vf[set][kb * 2 + s2] = *(const bf16x8*)(sVt + buf * 9216 + (32 * (vb) + ql) * 72 + 32 * kb + 16 * s2 + 8 * g); } while (0)
; __device__ __forceinline__ void phase_attn(const Params& p, unsigned char* lds) {
;     ...
;             bf16x8 P[2][2];
; #pragma unroll
;             for (int kb = 0; kb < 2; ++kb)
; #pragma unroll
;                 for (int s2 = 0; s2 < 2; ++s2) { u32x4 pk;
; #pragma unroll
;                     for (int jj = 0; jj < 4; ++jj) { const float p0 = __builtin_amdgcn_exp2f(st[kb][8 * s2 + 2 * jj] - mnew), p1 = __builtin_amdgcn_exp2f(st[kb][8 * s2 + 2 * jj + 1] - mnew); lsum += p0 + p1; pk[jj] = cvt_pk_bf16(p0, p1); }
;                     P[kb][s2] = __builtin_bit_cast(bf16x8, pk); }
;             {
;                 bf16x8 vf[2][4];
;     ...
;                 AT_LDV(0, 0);
; #pragma unroll
;                 for (int vb = 0; vb < 4; ++vb) {
;                     if (vb < 3) AT_LDV((vb + 1) & 1, vb + 1);
;                     __builtin_amdgcn_sched_barrier(0);
;                     __builtin_amdgcn_s_setprio(2);
; #pragma unroll
;                     for (int kb = 0; kb < 2; ++kb)
; #pragma unroll
;                         for (int s2 = 0; s2 < 2; ++s2) ot[vb] = __builtin_amdgcn_mfma_f32_32x32x16_bf16(vf[vb & 1][kb * 2 + s2], P[kb][s2], ot[vb], 0, 0, 0);
;                     __builtin_amdgcn_s_setprio(0);
;                     __builtin_amdgcn_sched_barrier(0);
;                 }
;     ...
;         lsum += __shfl_xor(lsum, 32);
.Lat_norescale_3:
	v_mov_b32_e32 v236, 0
	v_sub_f32_e32 v196, v196, v149
	v_sub_f32_e32 v197, v197, v149
	v_sub_f32_e32 v198, v198, v149
	v_sub_f32_e32 v199, v199, v149
	v_exp_f32_e32 v196, v196
	v_exp_f32_e32 v197, v197
	v_exp_f32_e32 v198, v198
	v_exp_f32_e32 v199, v199
	v_add_f32_e32 v128, v128, v196
	v_add_f32_e32 v236, v236, v197
	v_cvt_pk_bf16_f32 v196, v196, v197
	v_add_f32_e32 v128, v128, v198
	v_add_f32_e32 v236, v236, v199
	v_cvt_pk_bf16_f32 v197, v198, v199
	v_sub_f32_e32 v200, v200, v149
	v_sub_f32_e32 v201, v201, v149
	v_sub_f32_e32 v202, v202, v149
	v_sub_f32_e32 v203, v203, v149
	v_exp_f32_e32 v200, v200
	v_exp_f32_e32 v201, v201
	v_exp_f32_e32 v202, v202
	v_exp_f32_e32 v203, v203
	v_add_f32_e32 v128, v128, v200
	v_add_f32_e32 v236, v236, v201
	v_cvt_pk_bf16_f32 v198, v200, v201
	v_add_f32_e32 v128, v128, v202
	v_add_f32_e32 v236, v236, v203
	v_cvt_pk_bf16_f32 v199, v202, v203
	v_sub_f32_e32 v204, v204, v149
	v_sub_f32_e32 v205, v205, v149
	v_sub_f32_e32 v206, v206, v149
	v_sub_f32_e32 v207, v207, v149
	v_exp_f32_e32 v204, v204
	v_exp_f32_e32 v205, v205
	v_exp_f32_e32 v206, v206
	v_exp_f32_e32 v207, v207
	v_add_f32_e32 v128, v128, v204
	v_add_f32_e32 v236, v236, v205
	v_cvt_pk_bf16_f32 v200, v204, v205
	v_add_f32_e32 v128, v128, v206
	v_add_f32_e32 v236, v236, v207
	v_cvt_pk_bf16_f32 v201, v206, v207
	v_sub_f32_e32 v208, v208, v149
	v_sub_f32_e32 v209, v209, v149
	v_sub_f32_e32 v210, v210, v149
	v_sub_f32_e32 v211, v211, v149
	v_exp_f32_e32 v208, v208
	v_exp_f32_e32 v209, v209
	v_exp_f32_e32 v210, v210
	v_exp_f32_e32 v211, v211
	v_add_f32_e32 v128, v128, v208
	v_add_f32_e32 v236, v236, v209
	v_cvt_pk_bf16_f32 v202, v208, v209
	v_add_f32_e32 v128, v128, v210
	v_add_f32_e32 v236, v236, v211
	v_cvt_pk_bf16_f32 v203, v210, v211
	v_sub_f32_e32 v212, v212, v149
	v_sub_f32_e32 v213, v213, v149
	v_sub_f32_e32 v214, v214, v149
	v_sub_f32_e32 v215, v215, v149
	v_exp_f32_e32 v212, v212
	v_exp_f32_e32 v213, v213
	v_exp_f32_e32 v214, v214
	v_exp_f32_e32 v215, v215
	v_add_f32_e32 v128, v128, v212
	v_add_f32_e32 v236, v236, v213
	v_cvt_pk_bf16_f32 v212, v212, v213
	v_add_f32_e32 v128, v128, v214
	v_add_f32_e32 v236, v236, v215
	v_cvt_pk_bf16_f32 v213, v214, v215
	v_sub_f32_e32 v216, v216, v149
	v_sub_f32_e32 v217, v217, v149
	v_sub_f32_e32 v218, v218, v149
	v_sub_f32_e32 v219, v219, v149
	v_exp_f32_e32 v216, v216
	v_exp_f32_e32 v217, v217
	v_exp_f32_e32 v218, v218
	v_exp_f32_e32 v219, v219
	v_add_f32_e32 v128, v128, v216
	v_add_f32_e32 v236, v236, v217
	v_cvt_pk_bf16_f32 v214, v216, v217
	v_add_f32_e32 v128, v128, v218
	v_add_f32_e32 v236, v236, v219
	v_cvt_pk_bf16_f32 v215, v218, v219
	v_sub_f32_e32 v220, v220, v149
	v_sub_f32_e32 v221, v221, v149
	v_sub_f32_e32 v222, v222, v149
	v_sub_f32_e32 v223, v223, v149
	v_exp_f32_e32 v220, v220
	v_exp_f32_e32 v221, v221
	v_exp_f32_e32 v222, v222
	v_exp_f32_e32 v223, v223
	v_add_f32_e32 v128, v128, v220
	v_add_f32_e32 v236, v236, v221
	v_cvt_pk_bf16_f32 v216, v220, v221
	v_add_f32_e32 v128, v128, v222
	v_add_f32_e32 v236, v236, v223
	v_cvt_pk_bf16_f32 v217, v222, v223
	v_sub_f32_e32 v224, v224, v149
	v_sub_f32_e32 v225, v225, v149
	v_sub_f32_e32 v226, v226, v149
	v_sub_f32_e32 v227, v227, v149
	v_exp_f32_e32 v224, v224
	v_exp_f32_e32 v225, v225
	v_exp_f32_e32 v226, v226
	v_exp_f32_e32 v227, v227
	v_add_f32_e32 v128, v128, v224
	v_add_f32_e32 v236, v236, v225
	v_cvt_pk_bf16_f32 v218, v224, v225
	v_add_f32_e32 v128, v128, v226
	v_add_f32_e32 v236, v236, v227
	v_cvt_pk_bf16_f32 v219, v226, v227
	ds_read_b128 v[172:175], v147 offset:34816
	ds_read_b128 v[176:179], v147 offset:34848
	ds_read_b128 v[180:183], v147 offset:34880
	ds_read_b128 v[184:187], v147 offset:34912
	ds_read_b128 v[188:191], v147 offset:39424
	ds_read_b128 v[192:195], v147 offset:39456
	ds_read_b128 v[228:231], v147 offset:39488
	ds_read_b128 v[232:235], v147 offset:39520
	v_add_f32_e32 v128, v128, v236
	s_waitcnt lgkmcnt(7)
	v_mfma_f32_32x32x16_bf16 v[48:63], v[172:175], v[196:199], v[48:63]
	s_waitcnt lgkmcnt(6)
	v_mfma_f32_32x32x16_bf16 v[48:63], v[176:179], v[200:203], v[48:63]
	s_waitcnt lgkmcnt(5)
	v_mfma_f32_32x32x16_bf16 v[48:63], v[180:183], v[212:215], v[48:63]
	s_waitcnt lgkmcnt(4)
	v_mfma_f32_32x32x16_bf16 v[48:63], v[184:187], v[216:219], v[48:63]
	ds_read_b128 v[172:175], v147 offset:44032
	ds_read_b128 v[176:179], v147 offset:44064
	ds_read_b128 v[180:183], v147 offset:44096
	ds_read_b128 v[184:187], v147 offset:44128
	s_waitcnt lgkmcnt(7)
	v_mfma_f32_32x32x16_bf16 v[32:47], v[188:191], v[196:199], v[32:47]
	s_waitcnt lgkmcnt(6)
	v_mfma_f32_32x32x16_bf16 v[32:47], v[192:195], v[200:203], v[32:47]
	s_waitcnt lgkmcnt(5)
	v_mfma_f32_32x32x16_bf16 v[32:47], v[228:231], v[212:215], v[32:47]
	s_waitcnt lgkmcnt(4)
	v_mfma_f32_32x32x16_bf16 v[32:47], v[232:235], v[216:219], v[32:47]
	ds_read_b128 v[188:191], v147 offset:48640
	ds_read_b128 v[192:195], v147 offset:48672
	ds_read_b128 v[228:231], v147 offset:48704
	ds_read_b128 v[232:235], v147 offset:48736
	s_waitcnt lgkmcnt(7)
	v_mfma_f32_32x32x16_bf16 v[16:31], v[172:175], v[196:199], v[16:31]
	s_waitcnt lgkmcnt(6)
	v_mfma_f32_32x32x16_bf16 v[16:31], v[176:179], v[200:203], v[16:31]
	s_waitcnt lgkmcnt(5)
	v_mfma_f32_32x32x16_bf16 v[16:31], v[180:183], v[212:215], v[16:31]
	s_waitcnt lgkmcnt(4)
	v_mfma_f32_32x32x16_bf16 v[16:31], v[184:187], v[216:219], v[16:31]
	s_waitcnt lgkmcnt(3)
	v_mfma_f32_32x32x16_bf16 v[0:15], v[188:191], v[196:199], v[0:15]
	s_waitcnt lgkmcnt(2)
	v_mfma_f32_32x32x16_bf16 v[0:15], v[192:195], v[200:203], v[0:15]
	s_waitcnt lgkmcnt(1)
	v_mfma_f32_32x32x16_bf16 v[0:15], v[228:231], v[212:215], v[0:15]
	s_waitcnt lgkmcnt(0)
	v_mfma_f32_32x32x16_bf16 v[0:15], v[232:235], v[216:219], v[0:15]
	v_mov_b32_e32 v64, v128
	ds_bpermute_b32 v65, v158, v64
	s_waitcnt lgkmcnt(0)
	s_barrier
; __device__ __forceinline__ void phase_attn(const Params& p, unsigned char* lds) {
;     ...
;         lsum += __shfl_xor(lsum, 32);
;         const float inv = 1.0f / lsum;
;         if (cmap == 1) {
; #pragma unroll
;             for (int vb = 0; vb < 4; ++vb)
; #pragma unroll
;                 for (int i = 0; i < 16; ++i) ex[(vb * 16 + i) * 256 + qsub * 64 + lane] = ot[vb][i] * inv;
;         }
	v_add_f32_e32 v64, v64, v65
	v_div_scale_f32 v65, s[20:21], v64, v64, 1.0
	v_rcp_f32_e32 v66, v65
	v_div_scale_f32 v67, vcc, 1.0, v64, 1.0
	v_fma_f32 v68, -v65, v66, 1.0
	v_fmac_f32_e32 v66, v68, v66
	v_mul_f32_e32 v68, v67, v66
	v_fma_f32 v69, -v65, v68, v67
	v_fmac_f32_e32 v68, v69, v66
	v_fma_f32 v65, -v65, v68, v67
	v_div_fmas_f32 v65, v65, v66, v68
	v_div_fixup_f32 v64, v65, v64, 1.0
	s_and_saveexec_b64 s[20:21], s[4:5]
	s_cbranch_execz .LBB0_2029
	v_mul_f32_e32 v65, v48, v64
	v_mul_f32_e32 v66, v49, v64
	ds_write2st64_b32 v160, v65, v66 offset1:4
	v_mul_f32_e32 v65, v50, v64
	v_mul_f32_e32 v66, v51, v64
	ds_write2st64_b32 v160, v65, v66 offset0:8 offset1:12
	v_mul_f32_e32 v65, v52, v64
	v_mul_f32_e32 v66, v53, v64
	ds_write2st64_b32 v160, v65, v66 offset0:16 offset1:20
	v_mul_f32_e32 v65, v54, v64
	v_mul_f32_e32 v66, v55, v64
	ds_write2st64_b32 v160, v65, v66 offset0:24 offset1:28
	v_mul_f32_e32 v65, v56, v64
	v_mul_f32_e32 v66, v57, v64
	ds_write2st64_b32 v160, v65, v66 offset0:32 offset1:36
	v_mul_f32_e32 v65, v58, v64
	v_mul_f32_e32 v66, v59, v64
	ds_write2st64_b32 v160, v65, v66 offset0:40 offset1:44
	v_mul_f32_e32 v65, v60, v64
	v_mul_f32_e32 v66, v61, v64
	ds_write2st64_b32 v160, v65, v66 offset0:48 offset1:52
	v_mul_f32_e32 v65, v62, v64
	v_mul_f32_e32 v66, v63, v64
	ds_write2st64_b32 v160, v65, v66 offset0:56 offset1:60
	v_mul_f32_e32 v65, v32, v64
	v_mul_f32_e32 v66, v33, v64
	ds_write2st64_b32 v160, v65, v66 offset0:64 offset1:68
	v_mul_f32_e32 v65, v34, v64
	v_mul_f32_e32 v66, v35, v64
	ds_write2st64_b32 v160, v65, v66 offset0:72 offset1:76
	v_mul_f32_e32 v65, v36, v64
	v_mul_f32_e32 v66, v37, v64
	ds_write2st64_b32 v160, v65, v66 offset0:80 offset1:84
	v_mul_f32_e32 v65, v38, v64
	v_mul_f32_e32 v66, v39, v64
	ds_write2st64_b32 v160, v65, v66 offset0:88 offset1:92
	v_mul_f32_e32 v65, v40, v64
	v_mul_f32_e32 v66, v41, v64
	ds_write2st64_b32 v160, v65, v66 offset0:96 offset1:100
	v_mul_f32_e32 v65, v42, v64
	v_mul_f32_e32 v66, v43, v64
	ds_write2st64_b32 v160, v65, v66 offset0:104 offset1:108
	v_mul_f32_e32 v65, v44, v64
	v_mul_f32_e32 v66, v45, v64
	ds_write2st64_b32 v160, v65, v66 offset0:112 offset1:116
	v_mul_f32_e32 v65, v46, v64
	v_mul_f32_e32 v66, v47, v64
	ds_write2st64_b32 v160, v65, v66 offset0:120 offset1:124
	v_mul_f32_e32 v65, v16, v64
	v_mul_f32_e32 v66, v17, v64
	ds_write2st64_b32 v160, v65, v66 offset0:128 offset1:132
	v_mul_f32_e32 v65, v18, v64
	v_mul_f32_e32 v66, v19, v64
	ds_write2st64_b32 v160, v65, v66 offset0:136 offset1:140
	v_mul_f32_e32 v65, v20, v64
	v_mul_f32_e32 v66, v21, v64
	ds_write2st64_b32 v160, v65, v66 offset0:144 offset1:148
	v_mul_f32_e32 v65, v22, v64
	v_mul_f32_e32 v66, v23, v64
	ds_write2st64_b32 v160, v65, v66 offset0:152 offset1:156
	v_mul_f32_e32 v65, v24, v64
	v_mul_f32_e32 v66, v25, v64
	ds_write2st64_b32 v160, v65, v66 offset0:160 offset1:164
	v_mul_f32_e32 v65, v26, v64
	v_mul_f32_e32 v66, v27, v64
	ds_write2st64_b32 v160, v65, v66 offset0:168 offset1:172
	v_mul_f32_e32 v65, v28, v64
	v_mul_f32_e32 v66, v29, v64
	ds_write2st64_b32 v160, v65, v66 offset0:176 offset1:180
	v_mul_f32_e32 v65, v30, v64
	v_mul_f32_e32 v66, v31, v64
	ds_write2st64_b32 v160, v65, v66 offset0:184 offset1:188
	v_mul_f32_e32 v65, v0, v64
	v_mul_f32_e32 v66, v1, v64
	ds_write2st64_b32 v160, v65, v66 offset0:192 offset1:196
	v_mul_f32_e32 v65, v2, v64
	v_mul_f32_e32 v66, v3, v64
	ds_write2st64_b32 v160, v65, v66 offset0:200 offset1:204
	v_mul_f32_e32 v65, v4, v64
	v_mul_f32_e32 v66, v5, v64
	ds_write2st64_b32 v160, v65, v66 offset0:208 offset1:212
	v_mul_f32_e32 v65, v6, v64
	v_mul_f32_e32 v66, v7, v64
	ds_write2st64_b32 v160, v65, v66 offset0:216 offset1:220
	v_mul_f32_e32 v65, v8, v64
	v_mul_f32_e32 v66, v9, v64
	ds_write2st64_b32 v160, v65, v66 offset0:224 offset1:228
	v_mul_f32_e32 v65, v10, v64
	v_mul_f32_e32 v66, v11, v64
	ds_write2st64_b32 v160, v65, v66 offset0:232 offset1:236
	v_mul_f32_e32 v65, v12, v64
	v_mul_f32_e32 v66, v13, v64
	ds_write2st64_b32 v160, v65, v66 offset0:240 offset1:244
	v_mul_f32_e32 v65, v14, v64
	v_mul_f32_e32 v66, v15, v64
	ds_write2st64_b32 v160, v65, v66 offset0:248 offset1:252
